# back-edge rotation: the K-loop head's 9 scalar set-up instructions now run before the loop-back barrier (first K reads follow the barrier release directly); on top of the prologue DMA de-serialisation
# baseline (speedup 1.0000x reference)
; __device__ __forceinline__ void attn_dense_body(const bf16* Qb, const bf16* __restrict__ Kh, const bf16* __restrict__ Vh, const bf16* __restrict__ Zb, ...
;     ...
;   const TQ* Qw = Qb + (long)(wid * QBLK + r32) * LDQ + hi * 8;
; #pragma unroll
;   for (int d0 = 0; d0 < 8; ++d0) qr[d0] = SQ::tobf(SQ::ld8(Qw + d0 * 16));
;   float negBC;
;   { float ss = 0.f;
; #pragma unroll
;     for (int d0 = 0; d0 < 8; ++d0)
; #pragma unroll
;       for (int e = 0; e < 8; ++e) { const float qv = __uint_as_float((unsigned)(unsigned short)qr[d0][e] << 16); ss = fmaf(qv, qv, ss); }
;     auto rr = __builtin_amdgcn_permlane32_swap(__float_as_uint(ss), __float_as_uint(ss), false, false);
;     ss = __uint_as_float(rr[0]) + __uint_as_float(rr[1]);
;     negBC = -(sqrtf(ss) * kmax * (11.313708498984761f * 1.01f) + 0.07f); }
; __global__ void __launch_bounds__(NTHREADS, 2) mega(Params P) {
;     ...
;                 if (un < 1024) { b = un >> 9; h = (un >> 6) & 7; rowq = b * TB + CTXL + (un & 63) * 256; seq = TB; }
;                 else { const int c = un - 1024; b = c >> 3; h = c & 7; rowq = b * TB; seq = CTXL; }
;                 const size_t qoff = (size_t)rowq * DM + h * 128, koff = (size_t)b * TB * 256 + (h >> 2) * 128;
;                 att::attn_dense_body((const att::bf16*)(Q + qoff), (const att::bf16*)(Kb + koff), (const att::bf16*)(Vb + koff), (const att::bf16*)(ZA + qoff), (att::bf16*)(Q + qoff), seq, (char*)lds, wave, kmax, l3);
.LBB0_116:
	s_and_b32 s16, s15, 7
	s_ashr_i32 s25, s24, 31
	s_lshl_b64 s[24:25], s[24:25], 10
	s_lshl_b32 s16, s16, 7
	s_lshl_b32 s17, s15, 5
	s_or_b32 s24, s24, s16
	s_mul_i32 s16, s14, 0x410000
	s_and_b32 s17, s17, 0x80
	v_mov_b32_e32 v32, v236
	s_or_b32 s40, s16, s17
	s_lshl_b64 s[44:45], s[24:25], 1
	s_add_u32 s24, s8, s44
	v_and_b32_e32 v10, 31, v32
	v_ashrrev_i32_e32 v245, 5, v32
	v_or_b32_e32 v160, s69, v10
	s_addc_u32 s25, s9, s45
	v_lshlrev_b64 v[0:1], 11, v[160:161]
	v_lshlrev_b32_e32 v2, 3, v245
	v_lshl_add_u64 v[0:1], s[24:25], 0, v[0:1]
	v_ashrrev_i32_e32 v3, 31, v2
	v_lshl_add_u64 v[0:1], v[2:3], 1, v[0:1]
	flat_load_dwordx4 v[140:143], v[0:1]
	flat_load_dwordx4 v[136:139], v[0:1] offset:32
	flat_load_dwordx4 v[132:135], v[0:1] offset:64
	flat_load_dwordx4 v[128:131], v[0:1] offset:96
	flat_load_dwordx4 v[124:127], v[0:1] offset:128
	flat_load_dwordx4 v[120:123], v[0:1] offset:160
	flat_load_dwordx4 v[116:119], v[0:1] offset:192
	flat_load_dwordx4 v[112:115], v[0:1] offset:224
	s_mov_b32 s16, 0xf800000
	s_mul_hi_i32 s41, s14, 0x410000
	s_lshl_b64 s[40:41], s[40:41], 1
	s_add_u32 s46, s10, s40
	s_addc_u32 s47, s11, s41
	s_add_u32 s48, s12, s40
	s_addc_u32 s49, s13, s41
	s_add_i32 m0, s90, 0xc000
	v_mov_b32_e32 v146, 0
	s_mov_b32 s54, 0
	v_mov_b32_e32 v58, v146
	v_mov_b32_e32 v59, v146
	v_mov_b32_e32 v60, v146
	v_mov_b32_e32 v61, v146
	v_mov_b32_e32 v62, v146
	v_mov_b32_e32 v63, v146
	s_waitcnt vmcnt(0) lgkmcnt(0)
	v_lshlrev_b32_e32 v0, 16, v140
	v_and_b32_e32 v1, 0xffff0000, v140
	v_fma_f32 v0, v0, v0, 0
	v_lshlrev_b32_e32 v2, 16, v141
	v_fmac_f32_e32 v0, v1, v1
	v_and_b32_e32 v3, 0xffff0000, v141
	v_fmac_f32_e32 v0, v2, v2
	v_lshlrev_b32_e32 v4, 16, v142
	v_fmac_f32_e32 v0, v3, v3
	v_and_b32_e32 v5, 0xffff0000, v142
	v_fmac_f32_e32 v0, v4, v4
	v_lshlrev_b32_e32 v6, 16, v143
	v_fmac_f32_e32 v0, v5, v5
	v_and_b32_e32 v7, 0xffff0000, v143
	v_fmac_f32_e32 v0, v6, v6
	v_lshlrev_b32_e32 v8, 16, v136
	v_fmac_f32_e32 v0, v7, v7
	v_and_b32_e32 v9, 0xffff0000, v136
	v_fmac_f32_e32 v0, v8, v8
	v_lshlrev_b32_e32 v11, 16, v137
	v_fmac_f32_e32 v0, v9, v9
	v_and_b32_e32 v12, 0xffff0000, v137
	v_fmac_f32_e32 v0, v11, v11
	v_lshlrev_b32_e32 v13, 16, v138
	v_fmac_f32_e32 v0, v12, v12
	v_and_b32_e32 v14, 0xffff0000, v138
	v_fmac_f32_e32 v0, v13, v13
	v_lshlrev_b32_e32 v15, 16, v139
	v_fmac_f32_e32 v0, v14, v14
	v_and_b32_e32 v16, 0xffff0000, v139
	v_fmac_f32_e32 v0, v15, v15
	v_lshlrev_b32_e32 v17, 16, v132
	v_fmac_f32_e32 v0, v16, v16
	v_and_b32_e32 v18, 0xffff0000, v132
	v_fmac_f32_e32 v0, v17, v17
	v_lshlrev_b32_e32 v19, 16, v133
	v_fmac_f32_e32 v0, v18, v18
	v_and_b32_e32 v20, 0xffff0000, v133
	v_fmac_f32_e32 v0, v19, v19
	v_lshlrev_b32_e32 v21, 16, v134
	v_fmac_f32_e32 v0, v20, v20
	v_and_b32_e32 v22, 0xffff0000, v134
	v_fmac_f32_e32 v0, v21, v21
	v_lshlrev_b32_e32 v23, 16, v135
	v_fmac_f32_e32 v0, v22, v22
	v_and_b32_e32 v24, 0xffff0000, v135
	v_fmac_f32_e32 v0, v23, v23
	v_lshlrev_b32_e32 v25, 16, v128
	v_fmac_f32_e32 v0, v24, v24
	v_and_b32_e32 v26, 0xffff0000, v128
	v_fmac_f32_e32 v0, v25, v25
	v_lshlrev_b32_e32 v27, 16, v129
	v_fmac_f32_e32 v0, v26, v26
	v_and_b32_e32 v28, 0xffff0000, v129
	v_fmac_f32_e32 v0, v27, v27
	v_lshlrev_b32_e32 v29, 16, v130
	v_fmac_f32_e32 v0, v28, v28
	v_and_b32_e32 v30, 0xffff0000, v130
	v_fmac_f32_e32 v0, v29, v29
	v_lshlrev_b32_e32 v31, 16, v131
	v_fmac_f32_e32 v0, v30, v30
	v_and_b32_e32 v33, 0xffff0000, v131
	v_fmac_f32_e32 v0, v31, v31
	v_lshlrev_b32_e32 v34, 16, v124
	v_fmac_f32_e32 v0, v33, v33
	v_and_b32_e32 v35, 0xffff0000, v124
	v_fmac_f32_e32 v0, v34, v34
	v_lshlrev_b32_e32 v36, 16, v125
	v_fmac_f32_e32 v0, v35, v35
	v_and_b32_e32 v37, 0xffff0000, v125
	v_fmac_f32_e32 v0, v36, v36
	v_lshlrev_b32_e32 v38, 16, v126
	v_fmac_f32_e32 v0, v37, v37
	v_and_b32_e32 v39, 0xffff0000, v126
	v_fmac_f32_e32 v0, v38, v38
	v_lshlrev_b32_e32 v40, 16, v127
	v_fmac_f32_e32 v0, v39, v39
	v_and_b32_e32 v41, 0xffff0000, v127
	v_fmac_f32_e32 v0, v40, v40
	v_lshlrev_b32_e32 v42, 16, v120
	v_fmac_f32_e32 v0, v41, v41
	v_and_b32_e32 v43, 0xffff0000, v120
	v_fmac_f32_e32 v0, v42, v42
	v_lshlrev_b32_e32 v44, 16, v121
	v_fmac_f32_e32 v0, v43, v43
	v_and_b32_e32 v45, 0xffff0000, v121
	v_fmac_f32_e32 v0, v44, v44
	v_lshlrev_b32_e32 v46, 16, v122
	v_fmac_f32_e32 v0, v45, v45
	v_and_b32_e32 v47, 0xffff0000, v122
	v_fmac_f32_e32 v0, v46, v46
	v_lshlrev_b32_e32 v48, 16, v123
	v_fmac_f32_e32 v0, v47, v47
	v_and_b32_e32 v49, 0xffff0000, v123
	v_fmac_f32_e32 v0, v48, v48
	v_lshlrev_b32_e32 v50, 16, v116
	v_fmac_f32_e32 v0, v49, v49
	v_and_b32_e32 v51, 0xffff0000, v116
	v_fmac_f32_e32 v0, v50, v50
	v_lshlrev_b32_e32 v52, 16, v117
	v_fmac_f32_e32 v0, v51, v51
	v_and_b32_e32 v53, 0xffff0000, v117
	v_fmac_f32_e32 v0, v52, v52
	v_lshlrev_b32_e32 v54, 16, v118
	v_fmac_f32_e32 v0, v53, v53
	v_and_b32_e32 v55, 0xffff0000, v118
	v_fmac_f32_e32 v0, v54, v54
	v_lshlrev_b32_e32 v56, 16, v119
	v_fmac_f32_e32 v0, v55, v55
	v_and_b32_e32 v57, 0xffff0000, v119
	v_fmac_f32_e32 v0, v56, v56
	v_fmac_f32_e32 v0, v57, v57
	v_lshlrev_b32_e32 v1, 16, v112
	v_fmac_f32_e32 v0, v1, v1
	v_and_b32_e32 v1, 0xffff0000, v112
	v_fmac_f32_e32 v0, v1, v1
	v_lshlrev_b32_e32 v1, 16, v113
	v_fmac_f32_e32 v0, v1, v1
	v_and_b32_e32 v1, 0xffff0000, v113
	v_fmac_f32_e32 v0, v1, v1
	v_lshlrev_b32_e32 v1, 16, v114
	v_fmac_f32_e32 v0, v1, v1
	v_and_b32_e32 v1, 0xffff0000, v114
	v_fmac_f32_e32 v0, v1, v1
	v_lshlrev_b32_e32 v1, 16, v115
	v_fmac_f32_e32 v0, v1, v1
	v_and_b32_e32 v1, 0xffff0000, v115
	v_fmac_f32_e32 v0, v1, v1
	v_mov_b32_e32 v1, v0
	s_nop 1
	v_permlane32_swap_b32_e32 v0, v1
	v_add_f32_e32 v0, v0, v1
	v_mul_f32_e32 v1, 0x4f800000, v0
	v_cmp_gt_f32_e32 vcc, s16, v0
; __device__ __forceinline__ void partialSM3(f32x16& p0) { for (int r = 0; r < 16; ++r) p0[r] = __builtin_amdgcn_exp2f(p0[r]); }
; __device__ __forceinline__ int v_rd_base2(int lane) { return ((lane & 3) << 3) | (((lane >> 2) & 3) << 6) | (((lane >> 4) & 1) << 5) | (((lane >> 5) & 1) << 11); }
; #define DWAIT() asm volatile("s_waitcnt vmcnt(0)" ::: "memory")
; __device__ __forceinline__ void attn_dense_body(const bf16* Qb, const bf16* __restrict__ Kh, const bf16* __restrict__ Vh, const bf16* __restrict__ Zb, ...
;     ...
;     negBC = -(sqrtf(ss) * kmax * (11.313708498984761f * 1.01f) + 0.07f); }
;   f32x16 cinit; for (int r = 0; r < 16; ++r) cinit[r] = negBC;
;   const int vb0 = (int)(uintptr_t)V_lds + v_rd_base2(lane);
;   int koff0, koff1, voff0, voff1;
;   { const int rk0 = 8 * wid + (lane >> 4), rk1 = rk0 + 4; koff0 = rk0 * (LDK * 2) + (((lane & 15) ^ (rk0 & 15)) << 4); koff1 = rk1 * (LDK * 2) + (((lane & 15) ^ (rk1 & 15)) << 4);
;     const int st0 = 4 * wid + (lane >> 5), st1 = st0 + 2, q8 = (lane & 31) >> 2;
;     const int kk0 = ((st0 >> 2) << 3) | q8, kk1 = ((st1 >> 2) << 3) | q8;
;     const int ky0 = (kk0 & ~0xC) | ((kk0 & 4) << 1) | ((kk0 & 8) >> 1), ky1 = (kk1 & ~0xC) | ((kk1 & 4) << 1) | ((kk1 & 8) >> 1);
;     voff0 = ky0 * (LDK * 2) + ((st0 & 3) * 32 + (lane & 3) * 8) * 2; voff1 = ky1 * (LDK * 2) + ((st1 & 3) * 32 + (lane & 3) * 8) * 2; }
;     ...
;   f32x16 pA0, pA1, pB0, pB1; bf16x8 pa0, pa1, pa2, pa3; const int NT = seq / KVBLK;
;   SDMA(0, 0); DWAIT(); __syncthreads();
;   SDMA(1, KVBLK);
;   qkt3(pA0, pA1, K_lds, qr, r32, hi, cinit); partialSM3(pA0);
;   for (int r = 0; r < 16; ++r) pA1[r] = __builtin_amdgcn_exp2f(pA1[r]);
;   DWAIT(); __syncthreads();
	v_ashrrev_i32_e32 v43, 4, v32
	v_bfe_u32 v48, v32, 2, 2
	v_cndmask_b32_e32 v0, v0, v1, vcc
	v_sqrt_f32_e32 v1, v0
	v_lshlrev_b32_e32 v42, 4, v32
	v_lshlrev_b32_e32 v52, 4, v245
	v_lshlrev_b32_e32 v53, 8, v10
	v_add_u32_e32 v2, -1, v1
	v_fma_f32 v3, -v2, v1, v0
	v_cmp_ge_f32_e64 s[40:41], 0, v3
	v_add_u32_e32 v3, 1, v1
	v_and_b32_e32 v54, 0xf0, v42
	v_cndmask_b32_e64 v2, v1, v2, s[40:41]
	v_fma_f32 v1, -v3, v1, v0
	v_cmp_lt_f32_e64 s[40:41], 0, v1
	v_xad_u32 v157, v54, v52, v53
	s_movk_i32 s16, 0xc0
	v_cndmask_b32_e64 v1, v2, v3, s[40:41]
	v_mul_f32_e32 v2, 0x37800000, v1
	v_cndmask_b32_e32 v1, v1, v2, vcc
	v_cmp_class_f32_e32 vcc, v0, v233
	v_mov_b32_e32 v55, v146
	v_mov_b32_e32 v56, v146
	v_cndmask_b32_e32 v0, v1, v0, vcc
	v_mul_f32_e32 v0, v145, v0
	v_fmamk_f32 v0, v0, 0x4136d45c, v234
	v_xor_b32_e32 v64, 0x80000000, v0
	v_lshlrev_b32_e32 v0, 3, v32
	v_and_b32_e32 v33, 24, v0
	v_add_u32_e32 v0, s88, v43
	v_xor_b32_e32 v2, v0, v32
	v_add_u32_e32 v1, 4, v0
	v_lshlrev_b32_e32 v2, 4, v2
	v_and_b32_e32 v44, 0xf0, v2
	v_xor_b32_e32 v2, v1, v32
	v_lshlrev_b32_e32 v2, 4, v2
	v_and_b32_e32 v45, 0xf0, v2
	v_lshl_or_b32 v2, v1, 9, v45
	v_add_u32_e32 v1, s89, v245
	v_add_u32_e32 v3, 2, v1
	v_lshlrev_b32_e32 v4, 1, v1
	v_and_b32_e32 v46, -16, v4
	v_lshlrev_b32_e32 v4, 1, v3
	v_and_b32_e32 v47, -16, v4
	v_lshrrev_b32_e32 v4, 1, v32
	v_and_b32_e32 v51, 4, v3
	v_and_b32_e32 v49, 8, v4
	v_and_b32_e32 v50, 4, v1
	v_or_b32_e32 v4, v51, v47
	v_or_b32_e32 v1, v50, v46
	v_or3_b32 v5, v4, v48, v49
	v_and_or_b32 v4, v32, s93, v33
	v_or3_b32 v1, v1, v48, v49
	v_lshlrev_b32_e32 v4, 1, v4
	v_lshl_or_b32 v4, v1, 9, v4
	v_lshlrev_b32_e32 v1, 5, v3
	v_and_or_b32 v1, v1, s93, v33
	v_lshl_or_b32 v0, v0, 9, v44
	v_lshlrev_b32_e32 v1, 1, v1
	v_lshl_or_b32 v6, v5, 9, v1
	v_ashrrev_i32_e32 v1, 31, v0
	v_lshl_add_u64 v[8:9], s[46:47], 0, v[0:1]
	v_ashrrev_i32_e32 v3, 31, v2
	global_load_lds_dwordx4 v[8:9], off
	v_lshl_add_u64 v[8:9], s[46:47], 0, v[2:3]
	s_add_i32 m0, s90, 0xc400
	v_ashrrev_i32_e32 v5, 31, v4
	global_load_lds_dwordx4 v[8:9], off
	v_lshl_add_u64 v[8:9], s[48:49], 0, v[4:5]
	s_mov_b32 m0, s90
	v_ashrrev_i32_e32 v7, 31, v6
	global_load_lds_dwordx4 v[8:9], off
	s_add_i32 m0, s90, 0x400
	s_add_u32 s40, s46, 0x8000
	s_addc_u32 s41, s47, 0
	v_lshl_add_u64 v[8:9], s[48:49], 0, v[6:7]
	s_add_u32 s46, s48, 0x8000
	global_load_lds_dwordx4 v[8:9], off
	s_addc_u32 s47, s49, 0
	v_lshl_add_u64 v[0:1], s[40:41], 0, v[0:1]
	s_add_i32 m0, s90, 0x10000
	s_nop 0
	global_load_lds_dwordx4 v[0:1], off
	v_lshl_add_u64 v[0:1], s[40:41], 0, v[2:3]
	s_add_i32 m0, s90, 0x10400
	s_nop 0
	global_load_lds_dwordx4 v[0:1], off
	v_lshl_add_u64 v[0:1], s[46:47], 0, v[4:5]
	s_add_i32 m0, s90, 0x4000
	s_nop 0
	global_load_lds_dwordx4 v[0:1], off
	v_lshl_add_u64 v[0:1], s[46:47], 0, v[6:7]
	s_add_i32 m0, s90, 0x4400
	s_nop 0
	global_load_lds_dwordx4 v[0:1], off
	s_waitcnt vmcnt(0)
	s_waitcnt vmcnt(0) lgkmcnt(0)
	s_barrier
	v_mov_b32_e32 v65, v64
	v_add_u32_e32 v4, 0, v157
	v_mov_b32_e32 v66, v64
	ds_read_b128 v[0:3], v4 offset:49152
	ds_read_b128 v[34:37], v4 offset:57344
	v_mov_b32_e32 v67, v64
	v_mov_b32_e32 v68, v64
	v_mov_b32_e32 v69, v64
	v_mov_b32_e32 v70, v64
	v_mov_b32_e32 v71, v64
	v_mov_b32_e32 v72, v64
	v_mov_b32_e32 v73, v64
	v_mov_b32_e32 v74, v64
	v_mov_b32_e32 v75, v64
	v_mov_b32_e32 v76, v64
	v_mov_b32_e32 v77, v64
	v_mov_b32_e32 v78, v64
	v_mov_b32_e32 v79, v64
	s_cmp_lg_u32 0, -1
	s_mov_b32 s46, 1
	s_waitcnt lgkmcnt(0)
	v_mfma_f32_32x32x16_bf16 v[16:31], v[0:3], v[140:143], v[64:79]
	s_mov_b32 s47, 2
	s_mov_b32 s48, 2
	v_mov_b32_e32 v57, v146
	v_mfma_f32_32x32x16_bf16 v[0:15], v[34:37], v[140:143], v[64:79]
	v_add_u32_e32 v34, 32, v52
	v_xad_u32 v177, v34, v54, v53
	v_add_u32_e32 v38, 0, v177
	ds_read_b128 v[34:37], v38 offset:49152
	ds_read_b128 v[38:41], v38 offset:57344
	s_waitcnt lgkmcnt(0)
	v_mfma_f32_32x32x16_bf16 v[16:31], v[34:37], v[136:139], v[16:31]
	v_add_u32_e32 v34, 64, v52
	v_xad_u32 v175, v34, v54, v53
	v_mfma_f32_32x32x16_bf16 v[0:15], v[38:41], v[136:139], v[0:15]
	v_add_u32_e32 v38, 0, v175
	ds_read_b128 v[34:37], v38 offset:49152
	ds_read_b128 v[38:41], v38 offset:57344
	s_waitcnt lgkmcnt(0)
	v_mfma_f32_32x32x16_bf16 v[16:31], v[34:37], v[132:135], v[16:31]
	v_add_u32_e32 v34, 0x60, v52
	v_xad_u32 v173, v34, v54, v53
	v_mfma_f32_32x32x16_bf16 v[0:15], v[38:41], v[132:135], v[0:15]
	v_add_u32_e32 v38, 0, v173
	ds_read_b128 v[34:37], v38 offset:49152
	ds_read_b128 v[38:41], v38 offset:57344
	s_waitcnt lgkmcnt(0)
	v_mfma_f32_32x32x16_bf16 v[16:31], v[34:37], v[128:131], v[16:31]
	v_add_u32_e32 v34, 0x80, v52
	v_xad_u32 v171, v34, v54, v53
	v_mfma_f32_32x32x16_bf16 v[0:15], v[38:41], v[128:131], v[0:15]
	v_add_u32_e32 v38, 0, v171
	ds_read_b128 v[34:37], v38 offset:49152
	ds_read_b128 v[38:41], v38 offset:57344
	s_waitcnt lgkmcnt(0)
	v_mfma_f32_32x32x16_bf16 v[16:31], v[34:37], v[124:127], v[16:31]
	v_add_u32_e32 v34, 0xa0, v52
	v_xad_u32 v169, v34, v54, v53
	v_mfma_f32_32x32x16_bf16 v[0:15], v[38:41], v[124:127], v[0:15]
	v_add_u32_e32 v38, 0, v169
	ds_read_b128 v[34:37], v38 offset:49152
	ds_read_b128 v[38:41], v38 offset:57344
	s_waitcnt lgkmcnt(0)
	v_mfma_f32_32x32x16_bf16 v[16:31], v[34:37], v[120:123], v[16:31]
	v_add_u32_e32 v34, 0xc0, v52
	v_xad_u32 v167, v34, v54, v53
	v_mfma_f32_32x32x16_bf16 v[0:15], v[38:41], v[120:123], v[0:15]
	v_add_u32_e32 v38, 0, v167
	ds_read_b128 v[34:37], v38 offset:49152
	ds_read_b128 v[38:41], v38 offset:57344
	s_waitcnt lgkmcnt(0)
	v_mfma_f32_32x32x16_bf16 v[16:31], v[34:37], v[116:119], v[16:31]
	v_add_u32_e32 v34, 0xe0, v52
	v_xad_u32 v159, v34, v54, v53
	v_mov_b32_e32 v52, v146
	v_mov_b32_e32 v53, v146
	v_mov_b32_e32 v54, v146
	v_mfma_f32_32x32x16_bf16 v[0:15], v[38:41], v[116:119], v[0:15]
	v_add_u32_e32 v38, 0, v159
	ds_read_b128 v[34:37], v38 offset:49152
	ds_read_b128 v[38:41], v38 offset:57344
	s_waitcnt vmcnt(0)
	s_waitcnt vmcnt(0) lgkmcnt(0)
	s_barrier
; #define SBAR() __builtin_amdgcn_sched_barrier(0)
; __device__ __forceinline__ void partialSM3(f32x16& p0) { for (int r = 0; r < 16; ++r) p0[r] = __builtin_amdgcn_exp2f(p0[r]); }
; #define DWAIT() asm volatile("s_waitcnt vmcnt(0)" ::: "memory")
; __device__ __forceinline__ void attn_dense_body(const bf16* Qb, const bf16* __restrict__ Kh, const bf16* __restrict__ Vh, const bf16* __restrict__ Zb, ...
;     ...
;   qkt3(pA0, pA1, K_lds, qr, r32, hi, cinit); partialSM3(pA0);
;   for (int r = 0; r < 16; ++r) pA1[r] = __builtin_amdgcn_exp2f(pA1[r]);
;   DWAIT(); __syncthreads();
;   int sP = 0, sC = 1, sN = 2;
;     ...
;   for (int j = 1; j + 1 < NT; j += 2) {
;     SDMA(sN, (j + 1) * KVBLK);
;     SBAR(); qkt3(pB0, pB1, KSLOT(sC), qr, r32, hi, cinit);
	v_mfma_f32_32x32x16_bf16 v[0:15], v[38:41], v[112:115], v[0:15]
	v_mov_b32_e32 v38, v146
	v_mov_b32_e32 v39, v146
	v_mov_b32_e32 v40, v146
	v_mov_b32_e32 v41, v146
	s_nop 7
	v_exp_f32_e32 v168, v0
	v_mfma_f32_32x32x16_bf16 v[16:31], v[34:37], v[112:115], v[16:31]
	v_exp_f32_e32 v156, v1
	v_or_b32_e32 v0, v47, v49
	v_add_u16_e32 v1, 2, v245
	v_lshlrev_b32_e32 v34, 1, v32
	v_or3_b32 v0, v0, v51, v48
	v_and_b32_e32 v1, 3, v1
	v_and_b32_e32 v35, 32, v34
	v_lshlrev_b32_e32 v32, 6, v32
	v_exp_f32_e32 v158, v2
	v_lshlrev_b32_e32 v0, 9, v0
	v_lshlrev_b32_e32 v1, 6, v1
	v_and_b32_e32 v2, 48, v42
	v_and_or_b32 v35, v42, s16, v35
	v_and_b32_e32 v32, 0x800, v32
	v_or3_b32 v148, v0, v1, v2
	v_or_b32_e32 v0, v46, v49
	v_or3_b32 v32, v35, v32, v33
	s_cselect_b32 s16, 0, 0
	s_lshl_b32 s15, s15, 6
	v_or3_b32 v0, v0, v50, v48
	v_add_u32_e32 v147, s16, v32
	v_exp_f32_e32 v179, v16
	v_exp_f32_e32 v170, v17
	v_exp_f32_e32 v172, v18
	v_exp_f32_e32 v174, v19
	v_exp_f32_e32 v184, v20
	v_exp_f32_e32 v186, v21
	v_exp_f32_e32 v188, v22
	v_exp_f32_e32 v190, v23
	v_exp_f32_e32 v206, v24
	v_exp_f32_e32 v200, v25
	v_exp_f32_e32 v202, v26
	v_exp_f32_e32 v204, v27
	v_exp_f32_e32 v216, v28
	v_exp_f32_e32 v218, v29
	v_exp_f32_e32 v220, v30
	v_exp_f32_e32 v222, v31
	v_exp_f32_e32 v166, v3
	v_exp_f32_e32 v176, v4
	v_exp_f32_e32 v178, v5
	v_exp_f32_e32 v180, v6
	v_exp_f32_e32 v182, v7
	v_exp_f32_e32 v198, v8
	v_exp_f32_e32 v196, v9
	v_exp_f32_e32 v192, v10
	v_exp_f32_e32 v194, v11
	v_exp_f32_e32 v208, v12
	v_exp_f32_e32 v210, v13
	v_exp_f32_e32 v212, v14
	v_exp_f32_e32 v214, v15
	s_mul_hi_i32 s16, s14, 0x820000
	s_mul_i32 s14, s14, 0x820000
	s_and_b32 s15, s15, 0x100
	v_lshlrev_b32_e32 v0, 9, v0
	v_and_b32_e32 v1, 0xc0, v34
	s_or_b32 s14, s14, s15
	v_or3_b32 v150, v0, v1, v2
	v_lshlrev_b32_e32 v0, 9, v43
	s_add_u32 s40, s42, s14
	v_add3_u32 v152, s92, v0, v45
	v_add3_u32 v154, s63, v0, v44
	v_ashrrev_i32_e32 v149, 31, v148
	s_addc_u32 s41, s43, s16
	v_ashrrev_i32_e32 v151, 31, v150
	v_ashrrev_i32_e32 v153, 31, v152
	v_ashrrev_i32_e32 v155, 31, v154
	v_mov_b32_e32 v0, 0
	v_mov_b32_e32 v1, v146
	v_mov_b32_e32 v2, v146
	v_mov_b32_e32 v3, v146
	v_mov_b32_e32 v4, v146
	v_mov_b32_e32 v5, v146
	v_mov_b32_e32 v6, v146
	v_mov_b32_e32 v7, v146
	v_mov_b32_e32 v8, v146
	v_mov_b32_e32 v9, v146
	v_mov_b32_e32 v10, v146
	v_mov_b32_e32 v11, v146
	v_mov_b32_e32 v12, v146
	v_mov_b32_e32 v13, v146
	v_mov_b32_e32 v14, v146
	v_mov_b32_e32 v15, v146
	v_mov_b32_e32 v16, 0
	v_mov_b32_e32 v17, v146
	v_mov_b32_e32 v18, v146
	v_mov_b32_e32 v19, v146
	v_mov_b32_e32 v20, v146
	v_mov_b32_e32 v21, v146
	v_mov_b32_e32 v22, v146
	v_mov_b32_e32 v23, v146
	v_mov_b32_e32 v24, v146
	v_mov_b32_e32 v25, v146
	v_mov_b32_e32 v26, v146
	v_mov_b32_e32 v27, v146
	v_mov_b32_e32 v28, v146
	v_mov_b32_e32 v29, v146
	v_mov_b32_e32 v30, v146
	v_mov_b32_e32 v31, v146
	v_mov_b32_e32 v32, 0
	v_mov_b32_e32 v33, v146
	v_mov_b32_e32 v34, v146
	v_mov_b32_e32 v35, v146
	v_mov_b32_e32 v36, v146
	v_mov_b32_e32 v37, v146
	v_mov_b32_e32 v42, v146
	v_mov_b32_e32 v43, v146
	v_mov_b32_e32 v44, v146
	v_mov_b32_e32 v45, v146
	v_mov_b32_e32 v46, v146
	v_mov_b32_e32 v47, v146
	v_mov_b32_e32 v48, 0
	v_mov_b32_e32 v49, v146
	v_mov_b32_e32 v50, v146
	v_mov_b32_e32 v51, v146
	s_add_u32 s84, s40, s58
	s_addc_u32 s85, s41, s59
	s_add_u32 s40, s40, s70
	s_addc_u32 s41, s41, s71
	s_lshl_b32 s49, s48, 14
	s_mov_b32 s53, s46
	s_mov_b32 s46, s54
	s_add_i32 s86, s90, s49
	s_and_b32 s87, s47, 2
	s_lshl_b32 s87, s87, 14
	s_add_i32 s87, s87, s90
	s_lshl_b32 s15, s53, 14
	s_lshl_b32 s16, s54, 14
.LBB0_117:
	s_mov_b32 s14, s16
	v_add_u32_e32 v238, s15, v157
	ds_read_b128 v[246:249], v238 offset:49152
	ds_read_b128 v[238:241], v238 offset:57344
	v_add_u32_e32 v228, s15, v177
	ds_read_b128 v[224:227], v228 offset:49152
	ds_read_b128 v[228:231], v228 offset:57344
	v_cvt_pk_bf16_f32 v185, v202, v204
	v_cvt_pk_bf16_f32 v191, v180, v182
	v_cvt_pk_bf16_f32 v181, v212, v214
	v_cvt_pk_bf16_f32 v187, v220, v222
	v_cvt_pk_bf16_f32 v189, v158, v166
	s_waitcnt lgkmcnt(2)
	v_mfma_f32_32x32x16_bf16 v[96:111], v[246:249], v[140:143], v[64:79]
	v_mfma_f32_32x32x16_bf16 v[80:95], v[238:241], v[140:143], v[64:79]
	v_add_u32_e32 v238, s15, v175
	ds_read_b128 v[246:249], v238 offset:49152
	ds_read_b128 v[238:241], v238 offset:57344
	s_add_i32 m0, s86, 0xc000
	s_nop 0
	global_load_lds_dwordx4 v154, s[40:41]
	v_add_f32_e32 v162, 0, v179
	v_add_f32_e32 v162, v170, v162
	v_add_f32_e32 v162, v172, v162
	v_add_f32_e32 v162, v174, v162
	s_waitcnt lgkmcnt(2)
	v_mfma_f32_32x32x16_bf16 v[96:111], v[224:227], v[136:139], v[96:111]
	v_mfma_f32_32x32x16_bf16 v[80:95], v[228:231], v[136:139], v[80:95]
	v_add_u32_e32 v228, s15, v173
	ds_read_b128 v[224:227], v228 offset:49152
	ds_read_b128 v[228:231], v228 offset:57344
	v_add_f32_e32 v162, v184, v162
	v_add_f32_e32 v162, v186, v162
	v_add_f32_e32 v162, v188, v162
	v_add_f32_e32 v162, v190, v162
	s_waitcnt lgkmcnt(2)
	v_mfma_f32_32x32x16_bf16 v[96:111], v[246:249], v[132:135], v[96:111]
	v_mfma_f32_32x32x16_bf16 v[80:95], v[238:241], v[132:135], v[80:95]
	v_add_u32_e32 v238, s15, v171
	ds_read_b128 v[246:249], v238 offset:49152
	ds_read_b128 v[238:241], v238 offset:57344
	s_add_i32 m0, s86, 0xc400
	s_nop 0
	global_load_lds_dwordx4 v152, s[40:41]
	s_add_u32 s40, s40, 0x8000
	s_addc_u32 s41, s41, 0
	v_add_f32_e32 v162, v206, v162
	v_add_f32_e32 v162, v200, v162
	v_add_f32_e32 v162, v202, v162
	v_add_f32_e32 v162, v204, v162
	s_waitcnt lgkmcnt(2)
; #define SBAR() __builtin_amdgcn_sched_barrier(0)
; #define PK8(P, BASE, OUT) do { u32x4 w = {cvtpk(P[BASE + 0], P[BASE + 1]), cvtpk(P[BASE + 2], P[BASE + 3]), cvtpk(P[BASE + 4], P[BASE + 5]), cvtpk(P[BASE + 6], P[BASE + 7])}; OUT = *reinterpret_cast<bf16x8*>(&w); } while (0)
; #define PV_RD2(D0, X) const s16x4 X##l0 = tr_read<v_rd_off2(D0, 0, 0)>(vb), X##h0 = tr_read<v_rd_off2(D0, 0, 1)>(vb), X##l1 = tr_read<v_rd_off2(D0, 1, 0)>(vb), X##h1 = tr_read<v_rd_off2(D0, 1, 1)>(vb), \
;                               X##l2 = tr_read<v_rd_off2(D0, 2, 0)>(vb), X##h2 = tr_read<v_rd_off2(D0, 2, 1)>(vb), X##l3 = tr_read<v_rd_off2(D0, 3, 0)>(vb), X##h3 = tr_read<v_rd_off2(D0, 3, 1)>(vb)
; #define EXP4(P, B) do { P[(B) + 0] = __builtin_amdgcn_exp2f(P[(B) + 0]); P[(B) + 1] = __builtin_amdgcn_exp2f(P[(B) + 1]); P[(B) + 2] = __builtin_amdgcn_exp2f(P[(B) + 2]); P[(B) + 3] = __builtin_amdgcn_exp2f(P[(B) + 3]); } while (0)
; template <int FIRST> __device__ __forceinline__ void finishSM4(f32x16& p0, f32x16& p1, float& l_reg, bf16x8& pa0, bf16x8& pa1, bf16x8& pa2, bf16x8& pa3) {
;   for (int r = FIRST; r < 16; ++r) p1[r] = __builtin_amdgcn_exp2f(p1[r]);
;   float ps = 0; for (int r = 0; r < 16; ++r) ps += p0[r]; for (int r = 0; r < 16; ++r) ps += p1[r];
;   l_reg += ps;
;     ...
;   PK8(p0, 0, pa0); PK8(p0, 8, pa1); PK8(p1, 0, pa2); PK8(p1, 8, pa3);
;     ...
; }
; __device__ __forceinline__ void pv_d03(f32x16* o, int vb, bf16x8 pa0, bf16x8 pa1, bf16x8 pa2, bf16x8 pa3, f32x16& pn, f32x16& pm) {
;   PV_RD2(0, a);
;   PV_RD2(1, b); asm volatile("s_waitcnt lgkmcnt(8)" ::: "memory"); SBAR(); PV_MM2(o[0], a); EXP4(pn, 0); EXP4(pm, 0); SBAR();
;   PV_RD2(2, c); asm volatile("s_waitcnt lgkmcnt(8)" ::: "memory"); SBAR(); PV_MM2(o[1], b); EXP4(pn, 4); EXP4(pm, 4); SBAR();
;   PV_RD2(3, d); asm volatile("s_waitcnt lgkmcnt(8)" ::: "memory"); SBAR(); PV_MM2(o[2], c); EXP4(pn, 8); EXP4(pm, 8); SBAR();
;   asm volatile("s_waitcnt lgkmcnt(0)" ::: "memory"); SBAR(); PV_MM2(o[3], d); EXP4(pn, 12); EXP4(pm, 12);
; }
	v_mfma_f32_32x32x16_bf16 v[96:111], v[224:227], v[128:131], v[96:111]
	v_mfma_f32_32x32x16_bf16 v[80:95], v[228:231], v[128:131], v[80:95]
	v_add_u32_e32 v228, s15, v169
	ds_read_b128 v[224:227], v228 offset:49152
	ds_read_b128 v[228:231], v228 offset:57344
	v_add_f32_e32 v162, v216, v162
	v_add_f32_e32 v162, v218, v162
	v_add_f32_e32 v162, v220, v162
	v_add_f32_e32 v162, v222, v162
	s_waitcnt lgkmcnt(2)
	v_mfma_f32_32x32x16_bf16 v[96:111], v[246:249], v[124:127], v[96:111]
	v_mfma_f32_32x32x16_bf16 v[80:95], v[238:241], v[124:127], v[80:95]
	v_add_u32_e32 v238, s15, v167
	ds_read_b128 v[246:249], v238 offset:49152
	ds_read_b128 v[238:241], v238 offset:57344
	s_mov_b32 m0, s87
	s_nop 0
	global_load_lds_dwordx4 v150, s[84:85]
	v_add_f32_e32 v162, v168, v162
	v_add_f32_e32 v162, v156, v162
	v_add_f32_e32 v162, v158, v162
	v_add_f32_e32 v162, v166, v162
	s_waitcnt lgkmcnt(2)
	v_mfma_f32_32x32x16_bf16 v[96:111], v[224:227], v[120:123], v[96:111]
	v_mfma_f32_32x32x16_bf16 v[80:95], v[228:231], v[120:123], v[80:95]
	v_add_u32_e32 v228, s15, v159
	ds_read_b128 v[224:227], v228 offset:49152
	ds_read_b128 v[228:231], v228 offset:57344
	v_add_f32_e32 v162, v176, v162
	v_add_f32_e32 v162, v178, v162
	v_add_f32_e32 v162, v180, v162
	v_add_f32_e32 v162, v182, v162
	s_waitcnt lgkmcnt(2)
	v_mfma_f32_32x32x16_bf16 v[96:111], v[246:249], v[116:119], v[96:111]
	v_mfma_f32_32x32x16_bf16 v[80:95], v[238:241], v[116:119], v[80:95]
	s_add_i32 m0, s87, 0x400
	s_nop 0
	global_load_lds_dwordx4 v148, s[84:85]
	s_add_u32 s84, s84, 0x8000
	s_addc_u32 s85, s85, 0
	v_add_f32_e32 v162, v198, v162
	v_add_f32_e32 v162, v196, v162
	v_add_f32_e32 v162, v192, v162
	s_waitcnt lgkmcnt(0)
	v_mfma_f32_32x32x16_bf16 v[96:111], v[224:227], v[112:115], v[96:111]
	v_cvt_pk_bf16_f32 v238, v179, v170
	v_cvt_pk_bf16_f32 v179, v192, v194
	v_add_f32_e32 v162, v194, v162
	v_cvt_pk_bf16_f32 v241, v188, v190
	v_cvt_pk_bf16_f32 v190, v176, v178
	v_cvt_pk_bf16_f32 v178, v198, v196
	v_mfma_f32_32x32x16_bf16 v[80:95], v[228:231], v[112:115], v[80:95]
	s_bitcmp1_b32 s47, 1
	s_cselect_b32 s17, 0, 0x8000
	v_add_u32_e32 v246, s17, v147
	ds_read_b64_tr_b16 v[192:193], v246 offset:0
	ds_read_b64_tr_b16 v[194:195], v246 offset:0x100
	ds_read_b64_tr_b16 v[196:197], v246 offset:0x1000
	ds_read_b64_tr_b16 v[198:199], v246 offset:0x1100
	v_cvt_pk_bf16_f32 v240, v184, v186
	v_cvt_pk_bf16_f32 v184, v206, v200
	ds_read_b64_tr_b16 v[200:201], v246 offset:0x2000
	ds_read_b64_tr_b16 v[202:203], v246 offset:0x2100
	ds_read_b64_tr_b16 v[204:205], v246 offset:0x3000
	ds_read_b64_tr_b16 v[206:207], v246 offset:0x3100
	v_add_f32_e32 v162, v208, v162
	v_cvt_pk_bf16_f32 v180, v208, v210
	ds_read_b64_tr_b16 v[208:209], v246 offset:0x200
	v_add_f32_e32 v162, v210, v162
	ds_read_b64_tr_b16 v[210:211], v246 offset:0x300
	v_add_f32_e32 v162, v212, v162
	ds_read_b64_tr_b16 v[212:213], v246 offset:0x1200
	v_add_f32_e32 v162, v214, v162
	ds_read_b64_tr_b16 v[214:215], v246 offset:0x1300
	v_cvt_pk_bf16_f32 v186, v216, v218
	ds_read_b64_tr_b16 v[216:217], v246 offset:0x2200
	ds_read_b64_tr_b16 v[218:219], v246 offset:0x2300
	ds_read_b64_tr_b16 v[220:221], v246 offset:0x3200
	ds_read_b64_tr_b16 v[222:223], v246 offset:0x3300
	s_waitcnt lgkmcnt(8)
	v_add_f32_e32 v146, v146, v162
	v_cvt_pk_bf16_f32 v188, v168, v156
	v_cvt_pk_bf16_f32 v239, v172, v174
	s_nop 1
	v_mfma_f32_32x32x16_bf16 v[48:63], v[192:195], v[238:241], v[48:63]
	v_exp_f32_e32 v156, v96
	v_exp_f32_e32 v158, v97
	v_exp_f32_e32 v166, v82
	v_exp_f32_e32 v168, v83
	v_exp_f32_e32 v162, v98
	v_exp_f32_e32 v163, v99
	v_exp_f32_e32 v164, v80
	v_mfma_f32_32x32x16_bf16 v[48:63], v[196:199], v[184:187], v[48:63]
	v_exp_f32_e32 v165, v81
	v_mfma_f32_32x32x16_bf16 v[48:63], v[200:203], v[188:191], v[48:63]
	v_mfma_f32_32x32x16_bf16 v[48:63], v[204:207], v[178:181], v[48:63]
	ds_read_b64_tr_b16 v[80:81], v246 offset:0x400
	ds_read_b64_tr_b16 v[82:83], v246 offset:0x500
	ds_read_b64_tr_b16 v[96:97], v246 offset:0x1400
	ds_read_b64_tr_b16 v[98:99], v246 offset:0x1500
	ds_read_b64_tr_b16 v[192:193], v246 offset:0x2400
	ds_read_b64_tr_b16 v[194:195], v246 offset:0x2500
	ds_read_b64_tr_b16 v[196:197], v246 offset:0x3400
	ds_read_b64_tr_b16 v[198:199], v246 offset:0x3500
	s_waitcnt lgkmcnt(8)
	v_mfma_f32_32x32x16_bf16 v[32:47], v[208:211], v[238:241], v[32:47]
	v_exp_f32_e32 v170, v100
	v_exp_f32_e32 v172, v101
	v_exp_f32_e32 v174, v102
	v_exp_f32_e32 v176, v103
	v_mfma_f32_32x32x16_bf16 v[32:47], v[212:215], v[184:187], v[32:47]
	v_mfma_f32_32x32x16_bf16 v[32:47], v[216:219], v[188:191], v[32:47]
	v_exp_f32_e32 v216, v84
	v_exp_f32_e32 v218, v86
	v_exp_f32_e32 v217, v85
	v_exp_f32_e32 v219, v87
	v_mfma_f32_32x32x16_bf16 v[32:47], v[220:223], v[178:181], v[32:47]
	ds_read_b64_tr_b16 v[84:85], v246 offset:0x600
	ds_read_b64_tr_b16 v[86:87], v246 offset:0x700
	ds_read_b64_tr_b16 v[100:101], v246 offset:0x1600
	ds_read_b64_tr_b16 v[102:103], v246 offset:0x1700
	ds_read_b64_tr_b16 v[200:201], v246 offset:0x2600
	ds_read_b64_tr_b16 v[202:203], v246 offset:0x2700
	ds_read_b64_tr_b16 v[204:205], v246 offset:0x3600
	ds_read_b64_tr_b16 v[206:207], v246 offset:0x3700
	s_waitcnt lgkmcnt(8)
	v_mfma_f32_32x32x16_bf16 v[16:31], v[80:83], v[238:241], v[16:31]
	v_exp_f32_e32 v220, v88
	v_exp_f32_e32 v222, v90
	v_exp_f32_e32 v221, v89
	v_exp_f32_e32 v223, v91
	v_mfma_f32_32x32x16_bf16 v[16:31], v[96:99], v[184:187], v[16:31]
	v_mfma_f32_32x32x16_bf16 v[16:31], v[192:195], v[188:191], v[16:31]
	v_exp_f32_e32 v192, v104
	v_exp_f32_e32 v194, v106
	v_exp_f32_e32 v193, v105
	v_exp_f32_e32 v195, v107
	v_mfma_f32_32x32x16_bf16 v[16:31], v[196:199], v[178:181], v[16:31]
	s_waitcnt lgkmcnt(0)
	s_waitcnt vmcnt(0)
	s_barrier
; #define SBAR() __builtin_amdgcn_sched_barrier(0)
; __device__ __forceinline__ void qkt3(f32x16& p0, f32x16& p1, const bf16* Ks, const bf16x8* qr, int r32, int hi, const f32x16& cinit) {
;   { int cb = (hi * 8) * 2;
;     bf16x8 b0 = *reinterpret_cast<const bf16x8*>((const char*)Ks + KSWZ(r32, cb));
;     bf16x8 b1 = *reinterpret_cast<const bf16x8*>((const char*)Ks + KSWZ(32 + r32, cb));
;     p0 = __builtin_amdgcn_mfma_f32_32x32x16_bf16(b0, qr[0], cinit, 0, 0, 0);
;     p1 = __builtin_amdgcn_mfma_f32_32x32x16_bf16(b1, qr[0], cinit, 0, 0, 0); }
;   for (int d0 = 1; d0 < 8; ++d0) { int cb = (d0 * 16 + hi * 8) * 2;
;     bf16x8 b0 = *reinterpret_cast<const bf16x8*>((const char*)Ks + KSWZ(r32, cb));
;     bf16x8 b1 = *reinterpret_cast<const bf16x8*>((const char*)Ks + KSWZ(32 + r32, cb));
;     p0 = __builtin_amdgcn_mfma_f32_32x32x16_bf16(b0, qr[d0], p0, 0, 0, 0);
;     p1 = __builtin_amdgcn_mfma_f32_32x32x16_bf16(b1, qr[d0], p1, 0, 0, 0); }
; }
; __device__ __forceinline__ int v_st(int k, int c) { const int kk = (k & ~0xC) | ((k & 4) << 1) | ((k & 8) >> 1); return ((kk >> 3) * 4 + (c >> 5)) * 512 + ((kk & 7) * 32 + (c & 31)) * 2; }
; __device__ __forceinline__ int v_rd_base(int lane) { return ((lane & 3) << 3) | (((lane >> 2) & 3) << 6) | (((lane >> 4) & 1) << 5) | (((lane >> 5) & 1) << 8); }
; template <int OFF> __device__ __forceinline__ s16x4 tr_read(int vb) {
;   s16x4 r; asm volatile("ds_read_b64_tr_b16 %0, %1 offset:%2" : "=&v"(r) : "v"(vb), "i"(OFF) : "memory"); return r;
; }
; template <int D0> __device__ __forceinline__ void pv_one(f32x16& od, int vb, bf16x8 pa0, bf16x8 pa1, bf16x8 pa2, bf16x8 pa3) {
;   const s16x4 l0 = tr_read<v_rd_off(D0, 0, 0)>(vb), h0 = tr_read<v_rd_off(D0, 0, 1)>(vb), l1 = tr_read<v_rd_off(D0, 1, 0)>(vb), h1 = tr_read<v_rd_off(D0, 1, 1)>(vb);
;   const s16x4 l2 = tr_read<v_rd_off(D0, 2, 0)>(vb), h2 = tr_read<v_rd_off(D0, 2, 1)>(vb), l3 = tr_read<v_rd_off(D0, 3, 0)>(vb), h3 = tr_read<v_rd_off(D0, 3, 1)>(vb);
;   asm volatile("s_waitcnt lgkmcnt(0)" ::: "memory"); SBAR();
;     ...
;   od = __builtin_amdgcn_mfma_f32_32x32x16_bf16(pa0, PK(l0, h0), od, 0, 0, 0);
;   od = __builtin_amdgcn_mfma_f32_32x32x16_bf16(pa1, PK(l1, h1), od, 0, 0, 0);
;   od = __builtin_amdgcn_mfma_f32_32x32x16_bf16(pa2, PK(l2, h2), od, 0, 0, 0);
;   od = __builtin_amdgcn_mfma_f32_32x32x16_bf16(pa3, PK(l3, h3), od, 0, 0, 0);
;     ...
; }
	s_add_i32 s86, s90, s14
	s_mov_b32 s87, 0x4000
	s_bitcmp1_b32 s47, 1
	s_cselect_b32 s87, 0x18000, s87
	s_add_i32 s87, s87, s90
	v_mfma_f32_32x32x16_bf16 v[0:15], v[84:87], v[238:241], v[0:15]
	v_exp_f32_e32 v196, v94
	v_mfma_f32_32x32x16_bf16 v[0:15], v[100:103], v[184:187], v[0:15]
	v_exp_f32_e32 v186, v108
	v_exp_f32_e32 v187, v109
	v_exp_f32_e32 v197, v95
	v_mfma_f32_32x32x16_bf16 v[0:15], v[200:203], v[188:191], v[0:15]
	v_exp_f32_e32 v188, v110
	v_exp_f32_e32 v190, v92
	v_exp_f32_e32 v189, v111
	v_exp_f32_e32 v191, v93
	v_mfma_f32_32x32x16_bf16 v[0:15], v[204:207], v[178:181], v[0:15]
	s_add_i32 s16, s49, 0
	v_add_u32_e32 v182, s16, v157
	ds_read_b128 v[178:181], v182 offset:49152
	ds_read_b128 v[182:185], v182 offset:57344
	v_add_u32_e32 v246, s16, v177
	ds_read_b128 v[238:241], v246 offset:49152
	ds_read_b128 v[246:249], v246 offset:57344
	s_mov_b32 s17, 0x18000
	s_bitcmp1_b32 s47, 1
	s_cselect_b32 s17, 0x4000, s17
	v_add_u32_e32 v206, s17, v147
	v_cvt_pk_bf16_f32 v214, v186, v187
	v_cvt_pk_bf16_f32 v215, v188, v189
	v_cvt_pk_bf16_f32 v230, v190, v191
	v_cvt_pk_bf16_f32 v212, v192, v193
	s_waitcnt lgkmcnt(2)
	v_mfma_f32_32x32x16_bf16 v[96:111], v[178:181], v[140:143], v[64:79]
	v_mfma_f32_32x32x16_bf16 v[80:95], v[182:185], v[140:143], v[64:79]
	v_add_u32_e32 v182, s16, v175
	ds_read_b128 v[178:181], v182 offset:49152
	ds_read_b128 v[182:185], v182 offset:57344
	s_add_i32 m0, s86, 0xc000
	s_nop 0
	global_load_lds_dwordx4 v154, s[40:41]
	v_cvt_pk_bf16_f32 v213, v194, v195
	v_cvt_pk_bf16_f32 v231, v196, v197
	v_cvt_pk_bf16_f32 v226, v216, v217
	s_waitcnt lgkmcnt(2)
	v_mfma_f32_32x32x16_bf16 v[96:111], v[238:241], v[136:139], v[96:111]
	v_mfma_f32_32x32x16_bf16 v[80:95], v[246:249], v[136:139], v[80:95]
	v_add_u32_e32 v246, s16, v173
	ds_read_b128 v[238:241], v246 offset:49152
	ds_read_b128 v[246:249], v246 offset:57344
	v_cvt_pk_bf16_f32 v227, v218, v219
	v_cvt_pk_bf16_f32 v208, v156, v158
	v_cvt_pk_bf16_f32 v210, v170, v172
	s_waitcnt lgkmcnt(2)
	v_mfma_f32_32x32x16_bf16 v[96:111], v[178:181], v[132:135], v[96:111]
	v_mfma_f32_32x32x16_bf16 v[80:95], v[182:185], v[132:135], v[80:95]
	v_add_u32_e32 v182, s16, v171
	ds_read_b128 v[178:181], v182 offset:49152
	ds_read_b128 v[182:185], v182 offset:57344
	s_add_i32 m0, s86, 0xc400
	s_nop 0
	global_load_lds_dwordx4 v152, s[40:41]
	s_add_u32 s40, s40, 0x8000
	s_addc_u32 s41, s41, 0
	v_cvt_pk_bf16_f32 v209, v162, v163
	v_cvt_pk_bf16_f32 v211, v174, v176
	v_cvt_pk_bf16_f32 v224, v164, v165
	s_waitcnt lgkmcnt(2)
	v_mfma_f32_32x32x16_bf16 v[96:111], v[238:241], v[128:131], v[96:111]
	v_mfma_f32_32x32x16_bf16 v[80:95], v[246:249], v[128:131], v[80:95]
	v_add_u32_e32 v246, s16, v169
	ds_read_b128 v[238:241], v246 offset:49152
	ds_read_b128 v[246:249], v246 offset:57344
	v_cvt_pk_bf16_f32 v225, v166, v168
	v_cvt_pk_bf16_f32 v228, v220, v221
	v_cvt_pk_bf16_f32 v229, v222, v223
	s_waitcnt lgkmcnt(2)
	v_mfma_f32_32x32x16_bf16 v[96:111], v[178:181], v[124:127], v[96:111]
	v_mfma_f32_32x32x16_bf16 v[80:95], v[182:185], v[124:127], v[80:95]
	v_add_u32_e32 v182, s16, v167
	ds_read_b128 v[178:181], v182 offset:49152
	ds_read_b128 v[182:185], v182 offset:57344
	s_mov_b32 m0, s87
	s_nop 0
	global_load_lds_dwordx4 v150, s[84:85]
	s_waitcnt lgkmcnt(2)
	v_mfma_f32_32x32x16_bf16 v[96:111], v[238:241], v[120:123], v[96:111]
	v_mfma_f32_32x32x16_bf16 v[80:95], v[246:249], v[120:123], v[80:95]
	v_add_u32_e32 v246, s16, v159
	ds_read_b128 v[238:241], v246 offset:49152
	ds_read_b128 v[246:249], v246 offset:57344
	s_waitcnt lgkmcnt(2)
	v_mfma_f32_32x32x16_bf16 v[96:111], v[178:181], v[116:119], v[96:111]
	v_mfma_f32_32x32x16_bf16 v[80:95], v[182:185], v[116:119], v[80:95]
	s_add_i32 m0, s87, 0x400
	s_nop 0
	global_load_lds_dwordx4 v148, s[84:85]
	s_add_u32 s84, s84, 0x8000
	s_addc_u32 s85, s85, 0
	v_add_f32_e32 v178, 0, v156
	v_add_f32_e32 v178, v158, v178
	v_add_f32_e32 v178, v162, v178
	v_add_f32_e32 v178, v163, v178
	v_add_f32_e32 v178, v170, v178
	v_add_f32_e32 v178, v172, v178
	v_add_f32_e32 v178, v174, v178
	v_add_f32_e32 v178, v176, v178
	v_add_f32_e32 v178, v192, v178
	v_add_f32_e32 v178, v193, v178
	v_add_f32_e32 v178, v194, v178
	v_add_f32_e32 v178, v195, v178
	v_add_f32_e32 v178, v186, v178
	v_add_f32_e32 v178, v187, v178
	v_add_f32_e32 v178, v188, v178
	v_add_f32_e32 v178, v189, v178
	s_waitcnt lgkmcnt(0)
	v_mfma_f32_32x32x16_bf16 v[96:111], v[238:241], v[112:115], v[96:111]
	v_add_f32_e32 v178, v164, v178
	v_add_f32_e32 v178, v165, v178
	v_add_f32_e32 v178, v166, v178
	v_add_f32_e32 v178, v168, v178
	v_add_f32_e32 v178, v216, v178
	v_add_f32_e32 v178, v217, v178
	v_add_f32_e32 v178, v218, v178
	v_add_f32_e32 v178, v219, v178
	v_add_f32_e32 v178, v220, v178
	v_add_f32_e32 v178, v221, v178
	v_add_f32_e32 v178, v222, v178
	v_add_f32_e32 v178, v223, v178
	v_add_f32_e32 v178, v190, v178
	v_add_f32_e32 v178, v191, v178
	v_add_f32_e32 v178, v196, v178
	v_add_f32_e32 v178, v197, v178
	v_add_f32_e32 v146, v146, v178
	ds_read_b64_tr_b16 v[178:179], v206 offset:0
	ds_read_b64_tr_b16 v[180:181], v206 offset:0x100
	v_mfma_f32_32x32x16_bf16 v[80:95], v[246:249], v[112:115], v[80:95]
	ds_read_b64_tr_b16 v[182:183], v206 offset:0x1000
	ds_read_b64_tr_b16 v[184:185], v206 offset:0x1100
	ds_read_b64_tr_b16 v[186:187], v206 offset:0x2000
	ds_read_b64_tr_b16 v[188:189], v206 offset:0x2100
	ds_read_b64_tr_b16 v[190:191], v206 offset:0x3000
	ds_read_b64_tr_b16 v[192:193], v206 offset:0x3100
	ds_read_b64_tr_b16 v[194:195], v206 offset:0x200
	ds_read_b64_tr_b16 v[196:197], v206 offset:0x300
	ds_read_b64_tr_b16 v[198:199], v206 offset:0x1200
	ds_read_b64_tr_b16 v[200:201], v206 offset:0x1300
	ds_read_b64_tr_b16 v[202:203], v206 offset:0x2200
	ds_read_b64_tr_b16 v[204:205], v206 offset:0x2300
	ds_read_b64_tr_b16 v[216:217], v206 offset:0x3200
	ds_read_b64_tr_b16 v[218:219], v206 offset:0x3300
	s_waitcnt lgkmcnt(8)
; #define SBAR() __builtin_amdgcn_sched_barrier(0)
; #define PV_RD2(D0, X) const s16x4 X##l0 = tr_read<v_rd_off2(D0, 0, 0)>(vb), X##h0 = tr_read<v_rd_off2(D0, 0, 1)>(vb), X##l1 = tr_read<v_rd_off2(D0, 1, 0)>(vb), X##h1 = tr_read<v_rd_off2(D0, 1, 1)>(vb), \
;                               X##l2 = tr_read<v_rd_off2(D0, 2, 0)>(vb), X##h2 = tr_read<v_rd_off2(D0, 2, 1)>(vb), X##l3 = tr_read<v_rd_off2(D0, 3, 0)>(vb), X##h3 = tr_read<v_rd_off2(D0, 3, 1)>(vb)
; #define EXP4(P, B) do { P[(B) + 0] = __builtin_amdgcn_exp2f(P[(B) + 0]); P[(B) + 1] = __builtin_amdgcn_exp2f(P[(B) + 1]); P[(B) + 2] = __builtin_amdgcn_exp2f(P[(B) + 2]); P[(B) + 3] = __builtin_amdgcn_exp2f(P[(B) + 3]); } while (0)
; #define DWAIT() asm volatile("s_waitcnt vmcnt(0)" ::: "memory")
; #define ROT() do { const int t_ = sP; sP = sC; sC = sN; sN = t_; } while (0)
; __device__ __forceinline__ void pv_d03(f32x16* o, int vb, bf16x8 pa0, bf16x8 pa1, bf16x8 pa2, bf16x8 pa3, f32x16& pn, f32x16& pm) {
;   PV_RD2(0, a);
;   PV_RD2(1, b); asm volatile("s_waitcnt lgkmcnt(8)" ::: "memory"); SBAR(); PV_MM2(o[0], a); EXP4(pn, 0); EXP4(pm, 0); SBAR();
;   PV_RD2(2, c); asm volatile("s_waitcnt lgkmcnt(8)" ::: "memory"); SBAR(); PV_MM2(o[1], b); EXP4(pn, 4); EXP4(pm, 4); SBAR();
;   PV_RD2(3, d); asm volatile("s_waitcnt lgkmcnt(8)" ::: "memory"); SBAR(); PV_MM2(o[2], c); EXP4(pn, 8); EXP4(pm, 8); SBAR();
;   asm volatile("s_waitcnt lgkmcnt(0)" ::: "memory"); SBAR(); PV_MM2(o[3], d); EXP4(pn, 12); EXP4(pm, 12);
; }
; __device__ __forceinline__ void attn_dense_body(const bf16* Qb, const bf16* __restrict__ Kh, const bf16* __restrict__ Vh, const bf16* __restrict__ Zb, ...
;     ...
;     pv_d03(o, vb0 + sP * (int)SHM_V, pa0, pa1, pa2, pa3, pA0, pA1);
;     DWAIT(); __syncthreads(); ROT();
;   }
;   SBAR(); qkt3(pB0, pB1, KSLOT(sC), qr, r32, hi, cinit);
;   finishSM4<16>(pA0, pA1, l_reg, pa0, pa1, pa2, pa3); SBAR();
	v_mfma_f32_32x32x16_bf16 v[48:63], v[178:181], v[208:211], v[48:63]
	v_exp_f32_e32 v179, v96
	v_exp_f32_e32 v170, v97
	v_exp_f32_e32 v172, v98
	v_exp_f32_e32 v174, v99
	s_nop 6
	v_exp_f32_e32 v168, v80
	v_exp_f32_e32 v156, v81
	v_exp_f32_e32 v158, v82
	v_mfma_f32_32x32x16_bf16 v[48:63], v[182:185], v[212:215], v[48:63]
	v_exp_f32_e32 v166, v83
	v_mfma_f32_32x32x16_bf16 v[48:63], v[186:189], v[224:227], v[48:63]
	v_mfma_f32_32x32x16_bf16 v[48:63], v[190:193], v[228:231], v[48:63]
	ds_read_b64_tr_b16 v[80:81], v206 offset:0x400
	ds_read_b64_tr_b16 v[82:83], v206 offset:0x500
	ds_read_b64_tr_b16 v[96:97], v206 offset:0x1400
	ds_read_b64_tr_b16 v[98:99], v206 offset:0x1500
	ds_read_b64_tr_b16 v[220:221], v206 offset:0x2400
	ds_read_b64_tr_b16 v[222:223], v206 offset:0x2500
	ds_read_b64_tr_b16 v[238:239], v206 offset:0x3400
	ds_read_b64_tr_b16 v[240:241], v206 offset:0x3500
	s_waitcnt lgkmcnt(8)
	v_mfma_f32_32x32x16_bf16 v[32:47], v[194:197], v[208:211], v[32:47]
	v_exp_f32_e32 v184, v100
	v_exp_f32_e32 v186, v101
	v_exp_f32_e32 v188, v102
	v_exp_f32_e32 v190, v103
	v_exp_f32_e32 v176, v84
	v_exp_f32_e32 v178, v85
	v_exp_f32_e32 v180, v86
	v_mfma_f32_32x32x16_bf16 v[32:47], v[198:201], v[212:215], v[32:47]
	v_exp_f32_e32 v182, v87
	v_mfma_f32_32x32x16_bf16 v[32:47], v[202:205], v[224:227], v[32:47]
	v_mfma_f32_32x32x16_bf16 v[32:47], v[216:219], v[228:231], v[32:47]
	ds_read_b64_tr_b16 v[84:85], v206 offset:0x600
	ds_read_b64_tr_b16 v[86:87], v206 offset:0x700
	ds_read_b64_tr_b16 v[100:101], v206 offset:0x1600
	ds_read_b64_tr_b16 v[102:103], v206 offset:0x1700
	ds_read_b64_tr_b16 v[248:249], v206 offset:0x2600
	ds_read_b64_tr_b16 v[250:251], v206 offset:0x2700
	ds_read_b64_tr_b16 v[162:163], v206 offset:0x3600
	ds_read_b64_tr_b16 v[164:165], v206 offset:0x3700
	s_waitcnt lgkmcnt(8)
	v_mfma_f32_32x32x16_bf16 v[16:31], v[80:83], v[208:211], v[16:31]
	v_exp_f32_e32 v206, v104
	v_exp_f32_e32 v200, v105
	v_exp_f32_e32 v202, v106
	v_exp_f32_e32 v204, v107
	v_exp_f32_e32 v198, v88
	v_exp_f32_e32 v196, v89
	v_exp_f32_e32 v192, v90
	v_mfma_f32_32x32x16_bf16 v[16:31], v[96:99], v[212:215], v[16:31]
	v_exp_f32_e32 v194, v91
	v_mfma_f32_32x32x16_bf16 v[16:31], v[220:223], v[224:227], v[16:31]
	v_mfma_f32_32x32x16_bf16 v[16:31], v[238:241], v[228:231], v[16:31]
	s_waitcnt lgkmcnt(0)
	v_mfma_f32_32x32x16_bf16 v[0:15], v[84:87], v[208:211], v[0:15]
	v_exp_f32_e32 v216, v108
	v_exp_f32_e32 v218, v109
	v_exp_f32_e32 v220, v110
	v_exp_f32_e32 v222, v111
	v_exp_f32_e32 v208, v92
	v_exp_f32_e32 v210, v93
	v_mfma_f32_32x32x16_bf16 v[0:15], v[100:103], v[212:215], v[0:15]
	v_exp_f32_e32 v212, v94
	v_exp_f32_e32 v214, v95
	s_add_i32 s47, s47, 2
	s_mov_b32 s54, s48
	s_mov_b32 s48, s53
	v_mfma_f32_32x32x16_bf16 v[0:15], v[248:251], v[224:227], v[0:15]
	s_lshl_b32 s49, s48, 14
	s_mov_b32 s53, s46
	s_mov_b32 s46, s54
	s_add_i32 s86, s90, s49
	s_and_b32 s87, s47, 2
	s_lshl_b32 s87, s87, 14
	s_add_i32 s87, s87, s90
	s_lshl_b32 s15, s53, 14
	s_lshl_b32 s16, s54, 14
	s_waitcnt vmcnt(0)
	s_barrier
	s_cmp_lt_u32 s47, s52
	v_mfma_f32_32x32x16_bf16 v[0:15], v[162:165], v[228:231], v[0:15]
	s_cbranch_scc1 .LBB0_117
	s_add_u32 s40, s36, s44
	s_addc_u32 s41, s50, s45
	s_add_i32 s14, s14, 0
	v_add_u32_e32 v100, s14, v157
	ds_read_b128 v[96:99], v100 offset:49152
	v_add_u32_e32 v104, s14, v159
	v_add_f32_e32 v148, 0, v179
	v_cvt_pk_bf16_f32 v108, v179, v170
	v_cvt_pk_bf16_f32 v109, v172, v174
	v_cvt_pk_bf16_f32 v110, v184, v186
	v_cvt_pk_bf16_f32 v111, v188, v190
	s_waitcnt lgkmcnt(0)
	v_mfma_f32_32x32x16_bf16 v[80:95], v[96:99], v[140:143], v[64:79]
	ds_read_b128 v[96:99], v100 offset:57344
	v_add_u32_e32 v100, s14, v177
	s_waitcnt lgkmcnt(0)
	v_mfma_f32_32x32x16_bf16 v[64:79], v[96:99], v[140:143], v[64:79]
	ds_read_b128 v[96:99], v100 offset:49152
	s_waitcnt lgkmcnt(0)
	v_mfma_f32_32x32x16_bf16 v[80:95], v[96:99], v[136:139], v[80:95]
	ds_read_b128 v[96:99], v100 offset:57344
	v_add_u32_e32 v100, s14, v175
	s_waitcnt lgkmcnt(0)
	v_mfma_f32_32x32x16_bf16 v[64:79], v[96:99], v[136:139], v[64:79]
	ds_read_b128 v[96:99], v100 offset:49152
	s_waitcnt lgkmcnt(0)
	v_mfma_f32_32x32x16_bf16 v[80:95], v[96:99], v[132:135], v[80:95]
	ds_read_b128 v[96:99], v100 offset:57344
	v_add_u32_e32 v100, s14, v173
	s_waitcnt lgkmcnt(0)
	v_mfma_f32_32x32x16_bf16 v[64:79], v[96:99], v[132:135], v[64:79]
	ds_read_b128 v[96:99], v100 offset:49152
	s_waitcnt lgkmcnt(0)
	v_mfma_f32_32x32x16_bf16 v[80:95], v[96:99], v[128:131], v[80:95]
	ds_read_b128 v[96:99], v100 offset:57344
	v_add_u32_e32 v100, s14, v171
	s_waitcnt lgkmcnt(0)
	v_mfma_f32_32x32x16_bf16 v[64:79], v[96:99], v[128:131], v[64:79]
	ds_read_b128 v[96:99], v100 offset:49152
	s_waitcnt lgkmcnt(0)
	v_mfma_f32_32x32x16_bf16 v[80:95], v[96:99], v[124:127], v[80:95]
	ds_read_b128 v[96:99], v100 offset:57344
	v_add_u32_e32 v100, s14, v169
	s_waitcnt lgkmcnt(0)
	v_mfma_f32_32x32x16_bf16 v[64:79], v[96:99], v[124:127], v[64:79]
	ds_read_b128 v[96:99], v100 offset:49152
	s_waitcnt lgkmcnt(0)
	v_mfma_f32_32x32x16_bf16 v[80:95], v[96:99], v[120:123], v[80:95]
	ds_read_b128 v[96:99], v100 offset:57344
	v_add_u32_e32 v100, s14, v167
	s_waitcnt lgkmcnt(0)
	v_mfma_f32_32x32x16_bf16 v[64:79], v[96:99], v[120:123], v[64:79]
	ds_read_b128 v[96:99], v100 offset:49152
	s_waitcnt lgkmcnt(0)
	v_mfma_f32_32x32x16_bf16 v[80:95], v[96:99], v[116:119], v[80:95]
	ds_read_b128 v[96:99], v100 offset:57344
	ds_read_b128 v[100:103], v104 offset:49152
	ds_read_b128 v[104:107], v104 offset:57344
	s_waitcnt lgkmcnt(2)
; #define SBAR() __builtin_amdgcn_sched_barrier(0)
; #define PV_RD2(D0, X) const s16x4 X##l0 = tr_read<v_rd_off2(D0, 0, 0)>(vb), X##h0 = tr_read<v_rd_off2(D0, 0, 1)>(vb), X##l1 = tr_read<v_rd_off2(D0, 1, 0)>(vb), X##h1 = tr_read<v_rd_off2(D0, 1, 1)>(vb), \
;                               X##l2 = tr_read<v_rd_off2(D0, 2, 0)>(vb), X##h2 = tr_read<v_rd_off2(D0, 2, 1)>(vb), X##l3 = tr_read<v_rd_off2(D0, 3, 0)>(vb), X##h3 = tr_read<v_rd_off2(D0, 3, 1)>(vb)
; #define EXP4(P, B) do { P[(B) + 0] = __builtin_amdgcn_exp2f(P[(B) + 0]); P[(B) + 1] = __builtin_amdgcn_exp2f(P[(B) + 1]); P[(B) + 2] = __builtin_amdgcn_exp2f(P[(B) + 2]); P[(B) + 3] = __builtin_amdgcn_exp2f(P[(B) + 3]); } while (0)
; __device__ __forceinline__ void pv_d03(f32x16* o, int vb, bf16x8 pa0, bf16x8 pa1, bf16x8 pa2, bf16x8 pa3, f32x16& pn, f32x16& pm) {
;   PV_RD2(0, a);
;   PV_RD2(1, b); asm volatile("s_waitcnt lgkmcnt(8)" ::: "memory"); SBAR(); PV_MM2(o[0], a); EXP4(pn, 0); EXP4(pm, 0); SBAR();
;   PV_RD2(2, c); asm volatile("s_waitcnt lgkmcnt(8)" ::: "memory"); SBAR(); PV_MM2(o[1], b); EXP4(pn, 4); EXP4(pm, 4); SBAR();
;   PV_RD2(3, d); asm volatile("s_waitcnt lgkmcnt(8)" ::: "memory"); SBAR(); PV_MM2(o[2], c); EXP4(pn, 8); EXP4(pm, 8); SBAR();
;   asm volatile("s_waitcnt lgkmcnt(0)" ::: "memory"); SBAR(); PV_MM2(o[3], d); EXP4(pn, 12); EXP4(pm, 12);
; }
; __device__ __forceinline__ void attn_dense_body(const bf16* Qb, const bf16* __restrict__ Kh, const bf16* __restrict__ Vh, const bf16* __restrict__ Zb, ...
;     ...
;   finishSM4<16>(pA0, pA1, l_reg, pa0, pa1, pa2, pa3); SBAR();
;   pv_d03(o, vb0 + sP * (int)SHM_V, pa0, pa1, pa2, pa3, pB0, pB1);
;   finishSM4<16>(pB0, pB1, l_reg, pa0, pa1, pa2, pa3); SBAR();
	v_mfma_f32_32x32x16_bf16 v[64:79], v[96:99], v[116:119], v[64:79]
	v_cvt_pk_bf16_f32 v96, v206, v200
	v_cvt_pk_bf16_f32 v97, v202, v204
	v_cvt_pk_bf16_f32 v98, v216, v218
	v_cvt_pk_bf16_f32 v99, v220, v222
	v_cvt_pk_bf16_f32 v116, v198, v196
	v_cvt_pk_bf16_f32 v117, v192, v194
	v_cvt_pk_bf16_f32 v118, v208, v210
	s_waitcnt lgkmcnt(1)
	v_mfma_f32_32x32x16_bf16 v[80:95], v[100:103], v[112:115], v[80:95]
	v_cvt_pk_bf16_f32 v100, v168, v156
	v_cvt_pk_bf16_f32 v101, v158, v166
	v_cvt_pk_bf16_f32 v102, v176, v178
	v_cvt_pk_bf16_f32 v103, v180, v182
	v_cvt_pk_bf16_f32 v119, v212, v214
	s_waitcnt lgkmcnt(0)
	v_mfma_f32_32x32x16_bf16 v[64:79], v[104:107], v[112:115], v[64:79]
	s_mov_b32 s87, 0x18000
	s_bitcmp1_b32 s52, 1
	s_cselect_b32 s87, 0x4000, s87
	v_add_u32_e32 v246, s87, v147
	s_bitcmp1_b32 s52, 1
	s_cselect_b32 s87, 0, 0x8000
	v_add_u32_e32 v147, s87, v147
	ds_read_b64_tr_b16 v[104:105], v147 offset:0
	ds_read_b64_tr_b16 v[106:107], v147 offset:0x100
	ds_read_b64_tr_b16 v[112:113], v147 offset:0x1000
	ds_read_b64_tr_b16 v[114:115], v147 offset:0x1100
	ds_read_b64_tr_b16 v[120:121], v147 offset:0x2000
	ds_read_b64_tr_b16 v[122:123], v147 offset:0x2100
	ds_read_b64_tr_b16 v[124:125], v147 offset:0x3000
	ds_read_b64_tr_b16 v[126:127], v147 offset:0x3100
	ds_read_b64_tr_b16 v[128:129], v147 offset:0x200
	ds_read_b64_tr_b16 v[130:131], v147 offset:0x300
	ds_read_b64_tr_b16 v[132:133], v147 offset:0x1200
	ds_read_b64_tr_b16 v[134:135], v147 offset:0x1300
	ds_read_b64_tr_b16 v[136:137], v147 offset:0x2200
	ds_read_b64_tr_b16 v[138:139], v147 offset:0x2300
	ds_read_b64_tr_b16 v[140:141], v147 offset:0x3200
	ds_read_b64_tr_b16 v[142:143], v147 offset:0x3300
	s_waitcnt lgkmcnt(8)
	s_nop 0
	v_mfma_f32_32x32x16_bf16 v[48:63], v[104:107], v[108:111], v[48:63]
	s_nop 1
	v_exp_f32_e32 v171, v80
	v_exp_f32_e32 v173, v81
	v_exp_f32_e32 v175, v82
	v_exp_f32_e32 v185, v83
	s_nop 2
	v_exp_f32_e32 v157, v64
	v_exp_f32_e32 v159, v65
	v_exp_f32_e32 v167, v66
	v_mfma_f32_32x32x16_bf16 v[48:63], v[112:115], v[96:99], v[48:63]
	v_exp_f32_e32 v177, v67
	v_mfma_f32_32x32x16_bf16 v[48:63], v[120:123], v[100:103], v[48:63]
	v_mfma_f32_32x32x16_bf16 v[48:63], v[124:127], v[116:119], v[48:63]
	ds_read_b64_tr_b16 v[64:65], v147 offset:0x400
	ds_read_b64_tr_b16 v[66:67], v147 offset:0x500
	ds_read_b64_tr_b16 v[80:81], v147 offset:0x1400
	ds_read_b64_tr_b16 v[82:83], v147 offset:0x1500
	ds_read_b64_tr_b16 v[104:105], v147 offset:0x2400
	ds_read_b64_tr_b16 v[106:107], v147 offset:0x2500
	ds_read_b64_tr_b16 v[112:113], v147 offset:0x3400
	ds_read_b64_tr_b16 v[114:115], v147 offset:0x3500
	s_waitcnt lgkmcnt(8)
	v_mfma_f32_32x32x16_bf16 v[32:47], v[128:131], v[108:111], v[32:47]
	v_exp_f32_e32 v187, v84
	v_exp_f32_e32 v189, v85
	v_exp_f32_e32 v191, v86
	v_exp_f32_e32 v207, v87
	v_exp_f32_e32 v179, v68
	v_exp_f32_e32 v181, v69
	v_exp_f32_e32 v183, v70
	v_mfma_f32_32x32x16_bf16 v[32:47], v[132:135], v[96:99], v[32:47]
	v_exp_f32_e32 v199, v71
	v_mfma_f32_32x32x16_bf16 v[32:47], v[136:139], v[100:103], v[32:47]
	v_mfma_f32_32x32x16_bf16 v[32:47], v[140:143], v[116:119], v[32:47]
	ds_read_b64_tr_b16 v[68:69], v147 offset:0x600
	ds_read_b64_tr_b16 v[70:71], v147 offset:0x700
	ds_read_b64_tr_b16 v[84:85], v147 offset:0x1600
	ds_read_b64_tr_b16 v[86:87], v147 offset:0x1700
	ds_read_b64_tr_b16 v[120:121], v147 offset:0x2600
	ds_read_b64_tr_b16 v[122:123], v147 offset:0x2700
	ds_read_b64_tr_b16 v[124:125], v147 offset:0x3600
	ds_read_b64_tr_b16 v[126:127], v147 offset:0x3700
	s_waitcnt lgkmcnt(8)
	v_mfma_f32_32x32x16_bf16 v[16:31], v[64:67], v[108:111], v[16:31]
	v_exp_f32_e32 v201, v88
	v_exp_f32_e32 v203, v89
	v_exp_f32_e32 v205, v90
	v_exp_f32_e32 v217, v91
	v_exp_f32_e32 v197, v72
	v_exp_f32_e32 v193, v73
	v_exp_f32_e32 v195, v74
	v_mfma_f32_32x32x16_bf16 v[16:31], v[80:83], v[96:99], v[16:31]
	v_exp_f32_e32 v209, v75
	v_mfma_f32_32x32x16_bf16 v[16:31], v[104:107], v[100:103], v[16:31]
	v_mfma_f32_32x32x16_bf16 v[16:31], v[112:115], v[116:119], v[16:31]
	s_waitcnt lgkmcnt(0)
	v_mov_b32_e32 v149, v161
	v_add_f32_e64 v64, v170, v148
	v_add_f32_e64 v65, v171, v149
	v_mfma_f32_32x32x16_bf16 v[0:15], v[68:71], v[108:111], v[0:15]
	v_add_f32_e64 v64, v172, v64
	v_add_f32_e64 v65, v173, v65
	v_exp_f32_e32 v219, v92
	v_pk_add_f32 v[64:65], v[174:175], v[64:65]
	v_exp_f32_e32 v221, v93
	v_pk_add_f32 v[64:65], v[184:185], v[64:65]
	v_exp_f32_e32 v223, v94
	v_pk_add_f32 v[64:65], v[186:187], v[64:65]
	v_exp_f32_e32 v169, v95
	v_pk_add_f32 v[64:65], v[188:189], v[64:65]
	v_mfma_f32_32x32x16_bf16 v[0:15], v[84:87], v[96:99], v[0:15]
	v_add_f32_e64 v64, v190, v64
	v_add_f32_e64 v65, v191, v65
	v_exp_f32_e32 v211, v76
	v_pk_add_f32 v[64:65], v[206:207], v[64:65]
	v_exp_f32_e32 v213, v77
	v_pk_add_f32 v[64:65], v[200:201], v[64:65]
	v_exp_f32_e32 v215, v78
	v_pk_add_f32 v[64:65], v[202:203], v[64:65]
	v_mfma_f32_32x32x16_bf16 v[0:15], v[120:123], v[100:103], v[0:15]
	v_add_f32_e64 v64, v204, v64
	v_add_f32_e64 v65, v205, v65
	v_exp_f32_e32 v147, v79
	v_pk_add_f32 v[64:65], v[216:217], v[64:65]
	v_cvt_pk_bf16_f32 v66, v187, v189
	v_pk_add_f32 v[64:65], v[218:219], v[64:65]
	v_cvt_pk_bf16_f32 v67, v191, v207
	v_pk_add_f32 v[64:65], v[220:221], v[64:65]
	v_mfma_f32_32x32x16_bf16 v[0:15], v[124:127], v[116:119], v[0:15]
	v_add_f32_e64 v64, v222, v64
	v_add_f32_e64 v65, v223, v65
	v_cvt_pk_bf16_f32 v68, v201, v203
	v_add_f32_e64 v64, v168, v64
	v_add_f32_e64 v65, v169, v65
	v_cvt_pk_bf16_f32 v69, v205, v217
	v_pk_add_f32 v[64:65], v[156:157], v[64:65]
	v_cvt_pk_bf16_f32 v70, v219, v221
	v_pk_add_f32 v[64:65], v[158:159], v[64:65]
	v_cvt_pk_bf16_f32 v71, v223, v169
	v_pk_add_f32 v[64:65], v[166:167], v[64:65]
; #define SBAR() __builtin_amdgcn_sched_barrier(0)
; #define PK8(P, BASE, OUT) do { u32x4 w = {cvtpk(P[BASE + 0], P[BASE + 1]), cvtpk(P[BASE + 2], P[BASE + 3]), cvtpk(P[BASE + 4], P[BASE + 5]), cvtpk(P[BASE + 6], P[BASE + 7])}; OUT = *reinterpret_cast<bf16x8*>(&w); } while (0)
; #define PV_RD2(D0, X) const s16x4 X##l0 = tr_read<v_rd_off2(D0, 0, 0)>(vb), X##h0 = tr_read<v_rd_off2(D0, 0, 1)>(vb), X##l1 = tr_read<v_rd_off2(D0, 1, 0)>(vb), X##h1 = tr_read<v_rd_off2(D0, 1, 1)>(vb), \
;                               X##l2 = tr_read<v_rd_off2(D0, 2, 0)>(vb), X##h2 = tr_read<v_rd_off2(D0, 2, 1)>(vb), X##l3 = tr_read<v_rd_off2(D0, 3, 0)>(vb), X##h3 = tr_read<v_rd_off2(D0, 3, 1)>(vb)
; template <int FIRST> __device__ __forceinline__ void finishSM4(f32x16& p0, f32x16& p1, float& l_reg, bf16x8& pa0, bf16x8& pa1, bf16x8& pa2, bf16x8& pa3) {
;   for (int r = FIRST; r < 16; ++r) p1[r] = __builtin_amdgcn_exp2f(p1[r]);
;   float ps = 0; for (int r = 0; r < 16; ++r) ps += p0[r]; for (int r = 0; r < 16; ++r) ps += p1[r];
;   l_reg += ps;
;     ...
;   PK8(p0, 0, pa0); PK8(p0, 8, pa1); PK8(p1, 0, pa2); PK8(p1, 8, pa3);
;     ...
; }
; __device__ __forceinline__ void pv_d02(f32x16* o, int vb, bf16x8 pa0, bf16x8 pa1, bf16x8 pa2, bf16x8 pa3) {
;   PV_RD2(0, a);
;   PV_RD2(1, b); asm volatile("s_waitcnt lgkmcnt(8)" ::: "memory"); SBAR(); PV_MM2(o[0], a); SBAR();
;   PV_RD2(2, c); asm volatile("s_waitcnt lgkmcnt(8)" ::: "memory"); SBAR(); PV_MM2(o[1], b); SBAR();
;   PV_RD2(3, d); asm volatile("s_waitcnt lgkmcnt(8)" ::: "memory"); SBAR(); PV_MM2(o[2], c); SBAR();
;   asm volatile("s_waitcnt lgkmcnt(0)" ::: "memory"); SBAR(); PV_MM2(o[3], d);
; }
	v_cvt_pk_bf16_f32 v72, v157, v159
	v_pk_add_f32 v[64:65], v[176:177], v[64:65]
	v_cvt_pk_bf16_f32 v73, v167, v177
	v_pk_add_f32 v[64:65], v[178:179], v[64:65]
	v_cvt_pk_bf16_f32 v74, v179, v181
	v_pk_add_f32 v[64:65], v[180:181], v[64:65]
	v_cvt_pk_bf16_f32 v75, v183, v199
	v_pk_add_f32 v[64:65], v[182:183], v[64:65]
	v_cvt_pk_bf16_f32 v76, v197, v193
	v_pk_add_f32 v[64:65], v[198:199], v[64:65]
	v_cvt_pk_bf16_f32 v77, v195, v209
	v_pk_add_f32 v[64:65], v[196:197], v[64:65]
	v_cvt_pk_bf16_f32 v78, v211, v213
	v_pk_add_f32 v[64:65], v[192:193], v[64:65]
	v_cvt_pk_bf16_f32 v79, v215, v147
	v_pk_add_f32 v[64:65], v[194:195], v[64:65]
	s_nop 0
	v_pk_add_f32 v[64:65], v[208:209], v[64:65]
	s_nop 0
	v_pk_add_f32 v[64:65], v[210:211], v[64:65]
	s_nop 0
	v_pk_add_f32 v[64:65], v[212:213], v[64:65]
	s_nop 0
	v_pk_add_f32 v[64:65], v[214:215], v[64:65]
	s_nop 0
	v_pk_add_f32 v[64:65], v[146:147], v[64:65]
	s_nop 0
	v_pk_add_f32 v[112:113], v[64:65], v[64:65] op_sel:[0,1] op_sel_hi:[1,0]
	v_cvt_pk_bf16_f32 v64, v171, v173
	v_cvt_pk_bf16_f32 v65, v175, v185
	v_lshlrev_b32_e32 v222, 2, v245
	v_lshl_add_u32 v222, v160, 10, v222
	v_ashrrev_i32_e32 v223, 31, v222
	v_lshlrev_b64 v[222:223], 1, v[222:223]
	v_lshl_add_u64 v[220:221], s[40:41], 0, v[222:223]
	global_load_dwordx2 v[162:163], v[220:221], off
	global_load_dwordx2 v[164:165], v[220:221], off offset:16
	global_load_dwordx2 v[166:167], v[220:221], off offset:32
	global_load_dwordx2 v[168:169], v[220:221], off offset:48
	global_load_dwordx2 v[170:171], v[220:221], off offset:64
	global_load_dwordx2 v[172:173], v[220:221], off offset:80
	global_load_dwordx2 v[174:175], v[220:221], off offset:96
	global_load_dwordx2 v[176:177], v[220:221], off offset:112
	global_load_dwordx2 v[178:179], v[220:221], off offset:128
	global_load_dwordx2 v[180:181], v[220:221], off offset:144
	global_load_dwordx2 v[182:183], v[220:221], off offset:160
	global_load_dwordx2 v[184:185], v[220:221], off offset:176
	global_load_dwordx2 v[186:187], v[220:221], off offset:192
	global_load_dwordx2 v[188:189], v[220:221], off offset:208
	global_load_dwordx2 v[190:191], v[220:221], off offset:224
	global_load_dwordx2 v[192:193], v[220:221], off offset:240
	ds_read_b64_tr_b16 v[80:81], v246 offset:0
	ds_read_b64_tr_b16 v[82:83], v246 offset:0x100
	ds_read_b64_tr_b16 v[84:85], v246 offset:0x1000
	ds_read_b64_tr_b16 v[86:87], v246 offset:0x1100
	ds_read_b64_tr_b16 v[88:89], v246 offset:0x2000
	ds_read_b64_tr_b16 v[90:91], v246 offset:0x2100
	ds_read_b64_tr_b16 v[92:93], v246 offset:0x3000
	ds_read_b64_tr_b16 v[94:95], v246 offset:0x3100
	ds_read_b64_tr_b16 v[96:97], v246 offset:0x200
	ds_read_b64_tr_b16 v[98:99], v246 offset:0x300
	ds_read_b64_tr_b16 v[100:101], v246 offset:0x1200
	ds_read_b64_tr_b16 v[102:103], v246 offset:0x1300
	ds_read_b64_tr_b16 v[104:105], v246 offset:0x2200
	ds_read_b64_tr_b16 v[106:107], v246 offset:0x2300
	ds_read_b64_tr_b16 v[108:109], v246 offset:0x3200
	ds_read_b64_tr_b16 v[110:111], v246 offset:0x3300
	s_waitcnt lgkmcnt(8)
	s_nop 1
	v_mfma_f32_32x32x16_bf16 v[48:63], v[80:83], v[64:67], v[48:63]
	v_mfma_f32_32x32x16_bf16 v[48:63], v[84:87], v[68:71], v[48:63]
	v_mfma_f32_32x32x16_bf16 v[48:63], v[88:91], v[72:75], v[48:63]
	v_mfma_f32_32x32x16_bf16 v[48:63], v[92:95], v[76:79], v[48:63]
	ds_read_b64_tr_b16 v[80:81], v246 offset:0x400
	ds_read_b64_tr_b16 v[82:83], v246 offset:0x500
	ds_read_b64_tr_b16 v[84:85], v246 offset:0x1400
	ds_read_b64_tr_b16 v[86:87], v246 offset:0x1500
	ds_read_b64_tr_b16 v[88:89], v246 offset:0x2400
	ds_read_b64_tr_b16 v[90:91], v246 offset:0x2500
	ds_read_b64_tr_b16 v[92:93], v246 offset:0x3400
	ds_read_b64_tr_b16 v[94:95], v246 offset:0x3500
	s_waitcnt lgkmcnt(8)
	v_mfma_f32_32x32x16_bf16 v[32:47], v[96:99], v[64:67], v[32:47]
	v_mfma_f32_32x32x16_bf16 v[32:47], v[100:103], v[68:71], v[32:47]
	v_mfma_f32_32x32x16_bf16 v[32:47], v[104:107], v[72:75], v[32:47]
	v_mfma_f32_32x32x16_bf16 v[32:47], v[108:111], v[76:79], v[32:47]
	ds_read_b64_tr_b16 v[96:97], v246 offset:0x600
	ds_read_b64_tr_b16 v[98:99], v246 offset:0x700
	ds_read_b64_tr_b16 v[100:101], v246 offset:0x1600
	ds_read_b64_tr_b16 v[102:103], v246 offset:0x1700
	ds_read_b64_tr_b16 v[104:105], v246 offset:0x2600
	ds_read_b64_tr_b16 v[106:107], v246 offset:0x2700
	ds_read_b64_tr_b16 v[108:109], v246 offset:0x3600
	ds_read_b64_tr_b16 v[110:111], v246 offset:0x3700
	s_waitcnt lgkmcnt(8)
	v_mfma_f32_32x32x16_bf16 v[16:31], v[80:83], v[64:67], v[16:31]
	v_mfma_f32_32x32x16_bf16 v[16:31], v[84:87], v[68:71], v[16:31]
	v_mfma_f32_32x32x16_bf16 v[16:31], v[88:91], v[72:75], v[16:31]
	v_mfma_f32_32x32x16_bf16 v[16:31], v[92:95], v[76:79], v[16:31]
	s_waitcnt lgkmcnt(0)
; #define SBAR() __builtin_amdgcn_sched_barrier(0)
; __device__ __forceinline__ unsigned cvtpk(float lo, float hi) { return pg8::cvt_pk_bf16(lo, hi); }
; #define PV_RD2(D0, X) const s16x4 X##l0 = tr_read<v_rd_off2(D0, 0, 0)>(vb), X##h0 = tr_read<v_rd_off2(D0, 0, 1)>(vb), X##l1 = tr_read<v_rd_off2(D0, 1, 0)>(vb), X##h1 = tr_read<v_rd_off2(D0, 1, 1)>(vb), \
;                               X##l2 = tr_read<v_rd_off2(D0, 2, 0)>(vb), X##h2 = tr_read<v_rd_off2(D0, 2, 1)>(vb), X##l3 = tr_read<v_rd_off2(D0, 3, 0)>(vb), X##h3 = tr_read<v_rd_off2(D0, 3, 1)>(vb)
; __device__ __forceinline__ void pv_d02(f32x16* o, int vb, bf16x8 pa0, bf16x8 pa1, bf16x8 pa2, bf16x8 pa3) {
;   PV_RD2(0, a);
;   PV_RD2(1, b); asm volatile("s_waitcnt lgkmcnt(8)" ::: "memory"); SBAR(); PV_MM2(o[0], a); SBAR();
;   PV_RD2(2, c); asm volatile("s_waitcnt lgkmcnt(8)" ::: "memory"); SBAR(); PV_MM2(o[1], b); SBAR();
;   PV_RD2(3, d); asm volatile("s_waitcnt lgkmcnt(8)" ::: "memory"); SBAR(); PV_MM2(o[2], c); SBAR();
;   asm volatile("s_waitcnt lgkmcnt(0)" ::: "memory"); SBAR(); PV_MM2(o[3], d);
; }
; __device__ __forceinline__ void attn_dense_body(const bf16* Qb, const bf16* __restrict__ Kh, const bf16* __restrict__ Vh, const bf16* __restrict__ Zb, ...
;     ...
;   { auto rr = __builtin_amdgcn_permlane32_swap(__float_as_uint(l_reg), __float_as_uint(l_reg), false, false); l_reg = __uint_as_float(rr[0]) + __uint_as_float(rr[1]); }
;   const float rl = __builtin_amdgcn_rcpf(l_reg);
;   { int lb = (wid * QBLK + r32) * LDO + 4 * hi; asm volatile("" : "+v"(lb));
;     unsigned short* Ow = (unsigned short*)Ob + lb; const unsigned short* Zw = (const unsigned short*)Zb + lb;
; #pragma unroll
;     for (int d0 = 0; d0 < 4; ++d0)
; #pragma unroll
;       for (int g = 0; g < 4; ++g) { const int co = d0 * 32 + 8 * g; const unsigned long long zz = *(const unsigned long long*)(Zw + co);
;         const float z0 = __uint_as_float((unsigned)(zz << 16)), z1 = __uint_as_float((unsigned)zz & 0xffff0000u), z2 = __uint_as_float((unsigned)(zz >> 32) << 16), z3 = __uint_as_float((unsigned)(zz >> 32) & 0xffff0000u);
;         const unsigned w0 = cvtpk(o[d0][4 * g + 0] * rl * z0, o[d0][4 * g + 1] * rl * z1), w1 = cvtpk(o[d0][4 * g + 2] * rl * z2, o[d0][4 * g + 3] * rl * z3);
	v_mfma_f32_32x32x16_bf16 v[0:15], v[96:99], v[64:67], v[0:15]
	v_mov_b32_e32 v64, v112
	s_nop 1
	v_permlane32_swap_b32_e32 v112, v64
	v_add_f32_e32 v64, v112, v64
	s_add_i32 s51, s51, s62
	s_cmp_ge_i32 s51, s6
	v_mfma_f32_32x32x16_bf16 v[0:15], v[100:103], v[68:71], v[0:15]
	v_rcp_f32_e32 v68, v64
	v_lshlrev_b32_e32 v64, 2, v245
	v_lshl_add_u32 v64, v160, 10, v64
	v_ashrrev_i32_e32 v65, 31, v64
	v_lshlrev_b64 v[66:67], 1, v[64:65]
	v_lshl_add_u64 v[64:65], s[24:25], 0, v[66:67]
	v_mfma_f32_32x32x16_bf16 v[0:15], v[104:107], v[72:75], v[0:15]
	v_mfma_f32_32x32x16_bf16 v[0:15], v[108:111], v[76:79], v[0:15]
	v_mul_f32_e32 v48, v48, v68
	v_mul_f32_e32 v49, v49, v68
	v_mul_f32_e32 v50, v50, v68
	v_mul_f32_e32 v51, v51, v68
	v_mul_f32_e32 v52, v52, v68
	v_mul_f32_e32 v53, v53, v68
	v_mul_f32_e32 v54, v54, v68
	v_mul_f32_e32 v55, v55, v68
	v_mul_f32_e32 v56, v56, v68
	v_mul_f32_e32 v57, v57, v68
	v_mul_f32_e32 v58, v58, v68
	v_mul_f32_e32 v59, v59, v68
	v_mul_f32_e32 v60, v60, v68
	v_mul_f32_e32 v61, v61, v68
	v_mul_f32_e32 v62, v62, v68
	v_mul_f32_e32 v63, v63, v68
	v_mul_f32_e32 v32, v32, v68
	v_mul_f32_e32 v33, v33, v68
	v_mul_f32_e32 v34, v34, v68
	v_mul_f32_e32 v35, v35, v68
	v_mul_f32_e32 v36, v36, v68
	v_mul_f32_e32 v37, v37, v68
	v_mul_f32_e32 v38, v38, v68
	v_mul_f32_e32 v39, v39, v68
	v_mul_f32_e32 v40, v40, v68
	v_mul_f32_e32 v41, v41, v68
	v_mul_f32_e32 v42, v42, v68
	v_mul_f32_e32 v43, v43, v68
	v_mul_f32_e32 v44, v44, v68
	v_mul_f32_e32 v45, v45, v68
	v_mul_f32_e32 v46, v46, v68
	v_mul_f32_e32 v47, v47, v68
	v_mul_f32_e32 v16, v16, v68
	v_mul_f32_e32 v17, v17, v68
	v_mul_f32_e32 v18, v18, v68
	v_mul_f32_e32 v19, v19, v68
	v_mul_f32_e32 v20, v20, v68
	v_mul_f32_e32 v21, v21, v68
	v_mul_f32_e32 v22, v22, v68
	v_mul_f32_e32 v23, v23, v68
	v_mul_f32_e32 v24, v24, v68
	v_mul_f32_e32 v25, v25, v68
	v_mul_f32_e32 v26, v26, v68
	v_mul_f32_e32 v27, v27, v68
	v_mul_f32_e32 v28, v28, v68
	v_mul_f32_e32 v29, v29, v68
	v_mul_f32_e32 v30, v30, v68
	v_mul_f32_e32 v31, v31, v68
	v_mul_f32_e32 v0, v0, v68
	v_mul_f32_e32 v1, v1, v68
	v_mul_f32_e32 v2, v2, v68
	v_mul_f32_e32 v3, v3, v68
	v_mul_f32_e32 v4, v4, v68
	v_mul_f32_e32 v5, v5, v68
	v_mul_f32_e32 v6, v6, v68
	v_mul_f32_e32 v7, v7, v68
	v_mul_f32_e32 v8, v8, v68
	v_mul_f32_e32 v9, v9, v68
	v_mul_f32_e32 v10, v10, v68
	v_mul_f32_e32 v11, v11, v68
	v_mul_f32_e32 v12, v12, v68
	v_mul_f32_e32 v13, v13, v68
	v_mul_f32_e32 v14, v14, v68
	v_mul_f32_e32 v15, v15, v68
	s_waitcnt vmcnt(0)
; __device__ __forceinline__ unsigned cvtpk(float lo, float hi) { return pg8::cvt_pk_bf16(lo, hi); }
; __device__ __forceinline__ void attn_dense_body(const bf16* Qb, const bf16* __restrict__ Kh, const bf16* __restrict__ Vh, const bf16* __restrict__ Zb, ...
;     ...
;   { int lb = (wid * QBLK + r32) * LDO + 4 * hi; asm volatile("" : "+v"(lb));
;     unsigned short* Ow = (unsigned short*)Ob + lb; const unsigned short* Zw = (const unsigned short*)Zb + lb;
; #pragma unroll
;     for (int d0 = 0; d0 < 4; ++d0)
; #pragma unroll
;       for (int g = 0; g < 4; ++g) { const int co = d0 * 32 + 8 * g; const unsigned long long zz = *(const unsigned long long*)(Zw + co);
;         const float z0 = __uint_as_float((unsigned)(zz << 16)), z1 = __uint_as_float((unsigned)zz & 0xffff0000u), z2 = __uint_as_float((unsigned)(zz >> 32) << 16), z3 = __uint_as_float((unsigned)(zz >> 32) & 0xffff0000u);
;         const unsigned w0 = cvtpk(o[d0][4 * g + 0] * rl * z0, o[d0][4 * g + 1] * rl * z1), w1 = cvtpk(o[d0][4 * g + 2] * rl * z2, o[d0][4 * g + 3] * rl * z3);
;         *(unsigned long long*)(Ow + co) = (unsigned long long)w0 | ((unsigned long long)w1 << 32); } }
	v_lshlrev_b32_e32 v194, 16, v162
	v_and_b32_e32 v195, 0xffff0000, v162
	v_lshlrev_b32_e32 v196, 16, v163
	v_and_b32_e32 v197, 0xffff0000, v163
	v_mul_f32_e32 v48, v48, v194
	v_mul_f32_e32 v49, v49, v195
	v_mul_f32_e32 v50, v50, v196
	v_mul_f32_e32 v51, v51, v197
	v_cvt_pk_bf16_f32 v48, v48, v49
	v_cvt_pk_bf16_f32 v49, v50, v51
	global_store_dwordx2 v[64:65], v[48:49], off
	v_lshlrev_b32_e32 v194, 16, v164
	v_and_b32_e32 v195, 0xffff0000, v164
	v_lshlrev_b32_e32 v196, 16, v165
	v_and_b32_e32 v197, 0xffff0000, v165
	v_mul_f32_e32 v52, v52, v194
	v_mul_f32_e32 v53, v53, v195
	v_mul_f32_e32 v54, v54, v196
	v_mul_f32_e32 v55, v55, v197
	v_cvt_pk_bf16_f32 v52, v52, v53
	v_cvt_pk_bf16_f32 v53, v54, v55
	global_store_dwordx2 v[64:65], v[52:53], off offset:16
	v_lshlrev_b32_e32 v194, 16, v166
	v_and_b32_e32 v195, 0xffff0000, v166
	v_lshlrev_b32_e32 v196, 16, v167
	v_and_b32_e32 v197, 0xffff0000, v167
	v_mul_f32_e32 v56, v56, v194
	v_mul_f32_e32 v57, v57, v195
	v_mul_f32_e32 v58, v58, v196
	v_mul_f32_e32 v59, v59, v197
	v_cvt_pk_bf16_f32 v56, v56, v57
	v_cvt_pk_bf16_f32 v57, v58, v59
	global_store_dwordx2 v[64:65], v[56:57], off offset:32
	v_lshlrev_b32_e32 v194, 16, v168
	v_and_b32_e32 v195, 0xffff0000, v168
	v_lshlrev_b32_e32 v196, 16, v169
	v_and_b32_e32 v197, 0xffff0000, v169
	v_mul_f32_e32 v60, v60, v194
	v_mul_f32_e32 v61, v61, v195
	v_mul_f32_e32 v62, v62, v196
	v_mul_f32_e32 v63, v63, v197
	v_cvt_pk_bf16_f32 v60, v60, v61
	v_cvt_pk_bf16_f32 v61, v62, v63
	global_store_dwordx2 v[64:65], v[60:61], off offset:48
	v_lshlrev_b32_e32 v194, 16, v170
	v_and_b32_e32 v195, 0xffff0000, v170
	v_lshlrev_b32_e32 v196, 16, v171
	v_and_b32_e32 v197, 0xffff0000, v171
	v_mul_f32_e32 v32, v32, v194
	v_mul_f32_e32 v33, v33, v195
	v_mul_f32_e32 v34, v34, v196
	v_mul_f32_e32 v35, v35, v197
	v_cvt_pk_bf16_f32 v32, v32, v33
	v_cvt_pk_bf16_f32 v33, v34, v35
	global_store_dwordx2 v[64:65], v[32:33], off offset:64
	v_lshlrev_b32_e32 v194, 16, v172
	v_and_b32_e32 v195, 0xffff0000, v172
	v_lshlrev_b32_e32 v196, 16, v173
	v_and_b32_e32 v197, 0xffff0000, v173
	v_mul_f32_e32 v36, v36, v194
	v_mul_f32_e32 v37, v37, v195
	v_mul_f32_e32 v38, v38, v196
	v_mul_f32_e32 v39, v39, v197
	v_cvt_pk_bf16_f32 v36, v36, v37
	v_cvt_pk_bf16_f32 v37, v38, v39
	global_store_dwordx2 v[64:65], v[36:37], off offset:80
	v_lshlrev_b32_e32 v194, 16, v174
	v_and_b32_e32 v195, 0xffff0000, v174
	v_lshlrev_b32_e32 v196, 16, v175
	v_and_b32_e32 v197, 0xffff0000, v175
	v_mul_f32_e32 v40, v40, v194
	v_mul_f32_e32 v41, v41, v195
	v_mul_f32_e32 v42, v42, v196
	v_mul_f32_e32 v43, v43, v197
	v_cvt_pk_bf16_f32 v40, v40, v41
	v_cvt_pk_bf16_f32 v41, v42, v43
	global_store_dwordx2 v[64:65], v[40:41], off offset:96
	v_lshlrev_b32_e32 v194, 16, v176
	v_and_b32_e32 v195, 0xffff0000, v176
	v_lshlrev_b32_e32 v196, 16, v177
	v_and_b32_e32 v197, 0xffff0000, v177
	v_mul_f32_e32 v44, v44, v194
	v_mul_f32_e32 v45, v45, v195
	v_mul_f32_e32 v46, v46, v196
	v_mul_f32_e32 v47, v47, v197
	v_cvt_pk_bf16_f32 v44, v44, v45
	v_cvt_pk_bf16_f32 v45, v46, v47
	global_store_dwordx2 v[64:65], v[44:45], off offset:112
	v_lshlrev_b32_e32 v194, 16, v178
	v_and_b32_e32 v195, 0xffff0000, v178
	v_lshlrev_b32_e32 v196, 16, v179
	v_and_b32_e32 v197, 0xffff0000, v179
	v_mul_f32_e32 v16, v16, v194
	v_mul_f32_e32 v17, v17, v195
	v_mul_f32_e32 v18, v18, v196
	v_mul_f32_e32 v19, v19, v197
	v_cvt_pk_bf16_f32 v16, v16, v17
	v_cvt_pk_bf16_f32 v17, v18, v19
	global_store_dwordx2 v[64:65], v[16:17], off offset:128
	v_lshlrev_b32_e32 v194, 16, v180
	v_and_b32_e32 v195, 0xffff0000, v180
	v_lshlrev_b32_e32 v196, 16, v181
	v_and_b32_e32 v197, 0xffff0000, v181
	v_mul_f32_e32 v20, v20, v194
	v_mul_f32_e32 v21, v21, v195
	v_mul_f32_e32 v22, v22, v196
	v_mul_f32_e32 v23, v23, v197
	v_cvt_pk_bf16_f32 v20, v20, v21
	v_cvt_pk_bf16_f32 v21, v22, v23
	global_store_dwordx2 v[64:65], v[20:21], off offset:144
	v_lshlrev_b32_e32 v194, 16, v182
	v_and_b32_e32 v195, 0xffff0000, v182
	v_lshlrev_b32_e32 v196, 16, v183
	v_and_b32_e32 v197, 0xffff0000, v183
	v_mul_f32_e32 v24, v24, v194
	v_mul_f32_e32 v25, v25, v195
	v_mul_f32_e32 v26, v26, v196
	v_mul_f32_e32 v27, v27, v197
	v_cvt_pk_bf16_f32 v24, v24, v25
	v_cvt_pk_bf16_f32 v25, v26, v27
	global_store_dwordx2 v[64:65], v[24:25], off offset:160
	v_lshlrev_b32_e32 v194, 16, v184
	v_and_b32_e32 v195, 0xffff0000, v184
	v_lshlrev_b32_e32 v196, 16, v185
	v_and_b32_e32 v197, 0xffff0000, v185
	v_mul_f32_e32 v28, v28, v194
	v_mul_f32_e32 v29, v29, v195
	v_mul_f32_e32 v30, v30, v196
	v_mul_f32_e32 v31, v31, v197
	v_cvt_pk_bf16_f32 v28, v28, v29
	v_cvt_pk_bf16_f32 v29, v30, v31
	global_store_dwordx2 v[64:65], v[28:29], off offset:176
	v_lshlrev_b32_e32 v194, 16, v186
	v_and_b32_e32 v195, 0xffff0000, v186
	v_lshlrev_b32_e32 v196, 16, v187
	v_and_b32_e32 v197, 0xffff0000, v187
	v_mul_f32_e32 v0, v0, v194
	v_mul_f32_e32 v1, v1, v195
	v_mul_f32_e32 v2, v2, v196
	v_mul_f32_e32 v3, v3, v197
	v_cvt_pk_bf16_f32 v0, v0, v1
	v_cvt_pk_bf16_f32 v1, v2, v3
	global_store_dwordx2 v[64:65], v[0:1], off offset:192
	v_lshlrev_b32_e32 v194, 16, v188
	v_and_b32_e32 v195, 0xffff0000, v188
	v_lshlrev_b32_e32 v196, 16, v189
	v_and_b32_e32 v197, 0xffff0000, v189
	v_mul_f32_e32 v4, v4, v194
	v_mul_f32_e32 v5, v5, v195
	v_mul_f32_e32 v6, v6, v196
	v_mul_f32_e32 v7, v7, v197
	v_cvt_pk_bf16_f32 v4, v4, v5
	v_cvt_pk_bf16_f32 v5, v6, v7
	global_store_dwordx2 v[64:65], v[4:5], off offset:208
	v_lshlrev_b32_e32 v194, 16, v190
	v_and_b32_e32 v195, 0xffff0000, v190
	v_lshlrev_b32_e32 v196, 16, v191
	v_and_b32_e32 v197, 0xffff0000, v191
	v_mul_f32_e32 v8, v8, v194
	v_mul_f32_e32 v9, v9, v195
	v_mul_f32_e32 v10, v10, v196
	v_mul_f32_e32 v11, v11, v197
	v_cvt_pk_bf16_f32 v8, v8, v9
	v_cvt_pk_bf16_f32 v9, v10, v11
	global_store_dwordx2 v[64:65], v[8:9], off offset:224
	v_lshlrev_b32_e32 v194, 16, v192
	v_and_b32_e32 v195, 0xffff0000, v192
	v_lshlrev_b32_e32 v196, 16, v193
	v_and_b32_e32 v197, 0xffff0000, v193
	v_mul_f32_e32 v12, v12, v194
	v_mul_f32_e32 v13, v13, v195
	v_mul_f32_e32 v14, v14, v196
	v_mul_f32_e32 v15, v15, v197
	v_cvt_pk_bf16_f32 v12, v12, v13
	v_cvt_pk_bf16_f32 v13, v14, v15
	global_store_dwordx2 v[64:65], v[12:13], off offset:240
	s_cbranch_scc0 .LBB0_112
	v_readlane_b32 s84, v255, 16
	v_readlane_b32 s85, v255, 17
	v_readlane_b32 s86, v255, 18
	v_readlane_b32 s87, v255, 19
	s_nop 3
